# GEMM K-loops: loop-counter/pointer SALU moved ahead of the closing barrier (back-edge rotation lite)
# baseline (speedup 1.0000x reference)
; #define PG8_STAGE(bufoff, gbase, voff) do { _Pragma("unroll") for (int _i = 0; _i < 2; ++_i) \
;         __builtin_amdgcn_global_load_lds((const unsigned*)((const char*)(gbase) + (voff)[_i]), (PG8_LAS unsigned*)(lds + (bufoff) + ldsw + _i * 8192), 16, 0, 0); } while (0)
; #define PG8_LDA(dst, b, h) do { _Pragma("unroll") for (int m = 0; m < 4; ++m) _Pragma("unroll") for (int k = 0; k < 2; ++k) dst[m][k] = *(const PG8_LAS bf16x8*)(lds + PG8_SA(b, h) + aoff + m * 2048 + k * 1024); } while (0)
; #define PG8_LDB(dst, b, h) do { _Pragma("unroll") for (int n = 0; n < 2; ++n) _Pragma("unroll") for (int k = 0; k < 2; ++k) dst[n][k] = *(const PG8_LAS bf16x8*)(lds + PG8_SB(b, h) + boff + n * 2048 + k * 1024); } while (0)
; #define PG8_MMA(ai, bj, At, Bt) do { __builtin_amdgcn_s_setprio(1); _Pragma("unroll") for (int m = 0; m < 4; ++m) _Pragma("unroll") for (int n = 0; n < 2; ++n) _Pragma("unroll") for (int k = 0; k < 2; ++k) \
;         acc[ai][bj][m][n] = __builtin_amdgcn_mfma_f32_16x16x32_bf16(Bt[n][k], At[m][k], acc[ai][bj][m][n], 0, 0, 0); __builtin_amdgcn_s_setprio(0); } while (0)
; #define PG8_WAIT_V(n) asm volatile("s_waitcnt vmcnt(" #n ")" ::: "memory")
; #define PG8_WAIT_L(n) asm volatile("s_waitcnt lgkmcnt(" #n ")" ::: "memory")
; #define PG8_BAR __builtin_amdgcn_s_barrier()
; #define PG8_SCHED __builtin_amdgcn_sched_barrier(0)
; template <class Epi, class Sched, bool ALIGN_EPI = false, bool SP2 = false>
; __device__ __forceinline__ void gemm_phase(PG8_LAS unsigned char* lds, const Gemm g, const Sched& S, const Epi& E) {
;     ...
;             const bool last = (t == nt - 2);
;             const char* a1 = cA + (size_t)(t + 1) * kstep;
;             const char* a2 = last ? nA : cA + (size_t)(t + 2) * kstep; const char* b2 = last ? nB : cB + (size_t)(t + 2) * kstep;
;             const char* a3 = a2 + kstep; const char* b3 = b2 + kstep;
;             if (last && has_next) S.a_ready(nxt);
;             if constexpr (SP2) {
;             PG8_LDB(B0, 0, 0); PG8_LDB(B1, 0, 1); PG8_SCHED; PG8_LDA(At, 0, 0); PG8_STAGE(PG8_SA(1, 1), a1 + hstep, voffA);
;             PG8_WAIT_V(8); PG8_WAIT_L(0); PG8_BAR; PG8_MMA(0, 0, At, B0); PG8_MMA(0, 1, At, B1); PG8_BAR; PG8_SCHED;
;             PG8_LDA(At, 0, 1); PG8_STAGE(PG8_SB(0, 0), b2, voffB); PG8_STAGE(PG8_SB(0, 1), b2 + hstep, voffB); PG8_STAGE(PG8_SA(0, 0), a2, voffA);
.LBB0_212:
	s_add_u32 s4, s0, 0xfffc0080
	s_addc_u32 s5, s1, -1
	s_add_i32 s55, 0, 0x10000
	s_cmp_eq_u32 s58, 12
	s_cselect_b32 s15, s7, s5
	s_cselect_b32 s14, s25, s4
	s_cselect_b32 s5, s27, s57
	s_cselect_b32 s4, s54, s56
	s_add_i32 s59, 0, 0x14000
	s_waitcnt vmcnt(0) lgkmcnt(0)
	v_add_u32_e32 v44, s55, v196
	v_add_u32_e32 v156, s59, v196
	ds_read_b128 v[32:35], v44
	ds_read_b128 v[36:39], v44 offset:1024
	ds_read_b128 v[40:43], v44 offset:2048
	ds_read_b128 v[44:47], v44 offset:3072
	ds_read_b128 v[144:147], v156
	ds_read_b128 v[148:151], v156 offset:1024
	ds_read_b128 v[152:155], v156 offset:2048
	ds_read_b128 v[156:159], v156 offset:3072
	v_lshl_add_u64 v[194:195], s[0:1], 0, v[184:185]
	s_add_i32 m0, s37, 0xc000
	ds_read_b128 v[186:189], v199
	ds_read_b128 v[190:193], v199 offset:1024
	ds_read_b128 v[202:205], v199 offset:2048
	ds_read_b128 v[206:209], v199 offset:3072
	ds_read_b128 v[210:213], v199 offset:4096
	ds_read_b128 v[214:217], v199 offset:5120
	ds_read_b128 v[218:221], v199 offset:6144
	ds_read_b128 v[234:237], v199 offset:7168
	global_load_lds_dwordx4 v[194:195], off
	v_lshl_add_u64 v[194:195], s[0:1], 0, v[182:183]
	s_add_i32 m0, s37, 0xe000
	s_nop 0
	global_load_lds_dwordx4 v[194:195], off
	s_waitcnt vmcnt(8)
	s_waitcnt lgkmcnt(0)
	s_barrier
	s_setprio 1
	s_waitcnt lgkmcnt(0)
	v_mfma_f32_16x16x32_bf16 v[140:143], v[32:35], v[186:189], v[140:143]
	v_mfma_f32_16x16x32_bf16 v[136:139], v[40:43], v[186:189], v[136:139]
	v_mfma_f32_16x16x32_bf16 v[124:127], v[32:35], v[202:205], v[124:127]
	v_mfma_f32_16x16x32_bf16 v[120:123], v[40:43], v[202:205], v[120:123]
	v_mfma_f32_16x16x32_bf16 v[108:111], v[32:35], v[210:213], v[108:111]
	v_mfma_f32_16x16x32_bf16 v[104:107], v[40:43], v[210:213], v[104:107]
	v_mfma_f32_16x16x32_bf16 v[92:95], v[32:35], v[218:221], v[92:95]
	v_mfma_f32_16x16x32_bf16 v[88:91], v[40:43], v[218:221], v[88:91]
	v_mfma_f32_16x16x32_bf16 v[140:143], v[36:39], v[190:193], v[140:143]
	v_mfma_f32_16x16x32_bf16 v[136:139], v[44:47], v[190:193], v[136:139]
	v_mfma_f32_16x16x32_bf16 v[124:127], v[36:39], v[206:209], v[124:127]
	v_mfma_f32_16x16x32_bf16 v[120:123], v[44:47], v[206:209], v[120:123]
	v_mfma_f32_16x16x32_bf16 v[108:111], v[36:39], v[214:217], v[108:111]
	v_mfma_f32_16x16x32_bf16 v[104:107], v[44:47], v[214:217], v[104:107]
	v_mfma_f32_16x16x32_bf16 v[92:95], v[36:39], v[234:237], v[92:95]
	v_mfma_f32_16x16x32_bf16 v[88:91], v[44:47], v[234:237], v[88:91]
	s_setprio 0
	s_setprio 1
	v_mfma_f32_16x16x32_bf16 v[132:135], v[144:147], v[186:189], v[132:135]
	v_mfma_f32_16x16x32_bf16 v[128:131], v[152:155], v[186:189], v[128:131]
	v_mfma_f32_16x16x32_bf16 v[116:119], v[144:147], v[202:205], v[116:119]
	v_mfma_f32_16x16x32_bf16 v[112:115], v[152:155], v[202:205], v[112:115]
	v_mfma_f32_16x16x32_bf16 v[100:103], v[144:147], v[210:213], v[100:103]
	v_mfma_f32_16x16x32_bf16 v[96:99], v[152:155], v[210:213], v[96:99]
	v_mfma_f32_16x16x32_bf16 v[84:87], v[144:147], v[218:221], v[84:87]
	v_mfma_f32_16x16x32_bf16 v[80:83], v[152:155], v[218:221], v[80:83]
	v_mfma_f32_16x16x32_bf16 v[132:135], v[148:151], v[190:193], v[132:135]
	v_mfma_f32_16x16x32_bf16 v[128:131], v[156:159], v[190:193], v[128:131]
	v_mfma_f32_16x16x32_bf16 v[116:119], v[148:151], v[206:209], v[116:119]
	v_mfma_f32_16x16x32_bf16 v[112:115], v[156:159], v[206:209], v[112:115]
	v_mfma_f32_16x16x32_bf16 v[100:103], v[148:151], v[214:217], v[100:103]
	v_mfma_f32_16x16x32_bf16 v[96:99], v[156:159], v[214:217], v[96:99]
	v_mfma_f32_16x16x32_bf16 v[84:87], v[148:151], v[234:237], v[84:87]
	v_mfma_f32_16x16x32_bf16 v[80:83], v[156:159], v[234:237], v[80:83]
	s_setprio 0
	s_barrier
	s_add_i32 s55, s55, s44
	v_lshl_add_u64 v[194:195], s[4:5], 0, v[162:163]
	s_mov_b32 m0, s55
	ds_read_b128 v[186:189], v199 offset:16384
	ds_read_b128 v[190:193], v199 offset:17408
	ds_read_b128 v[202:205], v199 offset:18432
	ds_read_b128 v[206:209], v199 offset:19456
	ds_read_b128 v[210:213], v199 offset:20480
	ds_read_b128 v[214:217], v199 offset:21504
	ds_read_b128 v[218:221], v199 offset:22528
	ds_read_b128 v[234:237], v199 offset:23552
	global_load_lds_dwordx4 v[194:195], off
	s_add_i32 m0, s55, 0x2000
	s_add_u32 s60, s4, 0x40000
	v_lshl_add_u64 v[240:241], s[4:5], 0, v[166:167]
	s_addc_u32 s61, s5, 0
	s_add_i32 s55, s59, s44
	global_load_lds_dwordx4 v[240:241], off
	v_lshl_add_u64 v[242:243], s[60:61], 0, v[162:163]
	s_mov_b32 m0, s55
	v_lshl_add_u64 v[244:245], s[14:15], 0, v[164:165]
	global_load_lds_dwordx4 v[242:243], off
	v_lshl_add_u64 v[242:243], s[60:61], 0, v[166:167]
	s_add_i32 m0, s55, 0x2000
	s_nop 0
	global_load_lds_dwordx4 v[242:243], off
	v_lshl_add_u64 v[242:243], s[14:15], 0, v[160:161]
	s_mov_b32 m0, s37
	s_nop 0
	global_load_lds_dwordx4 v[242:243], off
	s_mov_b32 m0, s45
	s_nop 0
	global_load_lds_dwordx4 v[244:245], off
	s_waitcnt vmcnt(8)
	s_waitcnt lgkmcnt(0)
	s_barrier
; #define PG8_STAGE(bufoff, gbase, voff) do { _Pragma("unroll") for (int _i = 0; _i < 2; ++_i) \
;         __builtin_amdgcn_global_load_lds((const unsigned*)((const char*)(gbase) + (voff)[_i]), (PG8_LAS unsigned*)(lds + (bufoff) + ldsw + _i * 8192), 16, 0, 0); } while (0)
; #define PG8_LDA(dst, b, h) do { _Pragma("unroll") for (int m = 0; m < 4; ++m) _Pragma("unroll") for (int k = 0; k < 2; ++k) dst[m][k] = *(const PG8_LAS bf16x8*)(lds + PG8_SA(b, h) + aoff + m * 2048 + k * 1024); } while (0)
; #define PG8_LDB(dst, b, h) do { _Pragma("unroll") for (int n = 0; n < 2; ++n) _Pragma("unroll") for (int k = 0; k < 2; ++k) dst[n][k] = *(const PG8_LAS bf16x8*)(lds + PG8_SB(b, h) + boff + n * 2048 + k * 1024); } while (0)
; #define PG8_MMA(ai, bj, At, Bt) do { __builtin_amdgcn_s_setprio(1); _Pragma("unroll") for (int m = 0; m < 4; ++m) _Pragma("unroll") for (int n = 0; n < 2; ++n) _Pragma("unroll") for (int k = 0; k < 2; ++k) \
;         acc[ai][bj][m][n] = __builtin_amdgcn_mfma_f32_16x16x32_bf16(Bt[n][k], At[m][k], acc[ai][bj][m][n], 0, 0, 0); __builtin_amdgcn_s_setprio(0); } while (0)
; #define PG8_WAIT_V(n) asm volatile("s_waitcnt vmcnt(" #n ")" ::: "memory")
; #define PG8_WAIT_L(n) asm volatile("s_waitcnt lgkmcnt(" #n ")" ::: "memory")
; #define PG8_BAR __builtin_amdgcn_s_barrier()
; #define PG8_SCHED __builtin_amdgcn_sched_barrier(0)
; template <class Epi, class Sched, bool ALIGN_EPI = false, bool SP2 = false>
; __device__ __forceinline__ void gemm_phase(PG8_LAS unsigned char* lds, const Gemm g, const Sched& S, const Epi& E) {
;     ...
;             PG8_WAIT_V(8); PG8_WAIT_L(0); PG8_BAR; PG8_MMA(1, 0, At, B0); PG8_MMA(1, 1, At, B1); PG8_BAR; PG8_SCHED;
;             PG8_LDB(B0, 1, 0); PG8_LDB(B1, 1, 1); PG8_SCHED; PG8_LDA(At, 1, 0); PG8_STAGE(PG8_SA(0, 1), a2 + hstep, voffA);
;             PG8_WAIT_V(8); PG8_WAIT_L(0); PG8_BAR; PG8_MMA(0, 0, At, B0); PG8_MMA(0, 1, At, B1); PG8_BAR; PG8_SCHED;
	s_setprio 1
	s_waitcnt lgkmcnt(0)
	v_mfma_f32_16x16x32_bf16 v[76:79], v[32:35], v[186:189], v[76:79]
	v_mfma_f32_16x16x32_bf16 v[72:75], v[40:43], v[186:189], v[72:75]
	v_mfma_f32_16x16x32_bf16 v[60:63], v[32:35], v[202:205], v[60:63]
	v_mfma_f32_16x16x32_bf16 v[56:59], v[40:43], v[202:205], v[56:59]
	v_mfma_f32_16x16x32_bf16 v[28:31], v[32:35], v[210:213], v[28:31]
	v_mfma_f32_16x16x32_bf16 v[24:27], v[40:43], v[210:213], v[24:27]
	v_mfma_f32_16x16x32_bf16 v[12:15], v[32:35], v[218:221], v[12:15]
	v_mfma_f32_16x16x32_bf16 v[8:11], v[40:43], v[218:221], v[8:11]
	v_mfma_f32_16x16x32_bf16 v[76:79], v[36:39], v[190:193], v[76:79]
	v_mfma_f32_16x16x32_bf16 v[72:75], v[44:47], v[190:193], v[72:75]
	v_mfma_f32_16x16x32_bf16 v[60:63], v[36:39], v[206:209], v[60:63]
	v_mfma_f32_16x16x32_bf16 v[56:59], v[44:47], v[206:209], v[56:59]
	v_mfma_f32_16x16x32_bf16 v[28:31], v[36:39], v[214:217], v[28:31]
	v_mfma_f32_16x16x32_bf16 v[24:27], v[44:47], v[214:217], v[24:27]
	v_mfma_f32_16x16x32_bf16 v[12:15], v[36:39], v[234:237], v[12:15]
	v_mfma_f32_16x16x32_bf16 v[8:11], v[44:47], v[234:237], v[8:11]
	s_setprio 0
	s_setprio 1
	v_mfma_f32_16x16x32_bf16 v[20:23], v[144:147], v[210:213], v[20:23]
	v_mfma_f32_16x16x32_bf16 v[16:19], v[152:155], v[210:213], v[16:19]
	v_mfma_f32_16x16x32_bf16 v[4:7], v[144:147], v[218:221], v[4:7]
	v_mfma_f32_16x16x32_bf16 v[0:3], v[152:155], v[218:221], v[0:3]
	v_mfma_f32_16x16x32_bf16 v[32:35], v[144:147], v[186:189], v[68:71]
	v_mfma_f32_16x16x32_bf16 v[36:39], v[152:155], v[186:189], v[64:67]
	v_mfma_f32_16x16x32_bf16 v[40:43], v[144:147], v[202:205], v[52:55]
	v_mfma_f32_16x16x32_bf16 v[44:47], v[152:155], v[202:205], v[48:51]
	v_mfma_f32_16x16x32_bf16 v[20:23], v[148:151], v[214:217], v[20:23]
	v_mfma_f32_16x16x32_bf16 v[16:19], v[156:159], v[214:217], v[16:19]
	v_mfma_f32_16x16x32_bf16 v[4:7], v[148:151], v[234:237], v[4:7]
	v_mfma_f32_16x16x32_bf16 v[0:3], v[156:159], v[234:237], v[0:3]
	v_mfma_f32_16x16x32_bf16 v[32:35], v[148:151], v[190:193], v[32:35]
	v_mfma_f32_16x16x32_bf16 v[36:39], v[156:159], v[190:193], v[36:39]
	v_mfma_f32_16x16x32_bf16 v[40:43], v[148:151], v[206:209], v[40:43]
	v_mfma_f32_16x16x32_bf16 v[44:47], v[156:159], v[206:209], v[44:47]
	s_setprio 0
	s_barrier
	s_add_i32 s55, 0, 0x18000
	s_add_i32 s59, 0, 0x1c000
	v_add_u32_e32 v68, s55, v196
	v_add_u32_e32 v156, s59, v196
	ds_read_b128 v[48:51], v68
	ds_read_b128 v[52:55], v68 offset:1024
	ds_read_b128 v[64:67], v68 offset:2048
	ds_read_b128 v[68:71], v68 offset:3072
	ds_read_b128 v[144:147], v156
	ds_read_b128 v[148:151], v156 offset:1024
	ds_read_b128 v[152:155], v156 offset:2048
	ds_read_b128 v[156:159], v156 offset:3072
	s_add_u32 s14, s14, 0x40000
	s_addc_u32 s15, s15, 0
	s_mov_b32 m0, s49
	v_lshl_add_u64 v[246:247], s[14:15], 0, v[160:161]
	ds_read_b128 v[186:189], v199 offset:32768
	ds_read_b128 v[190:193], v199 offset:33792
	ds_read_b128 v[202:205], v199 offset:34816
	ds_read_b128 v[206:209], v199 offset:35840
	ds_read_b128 v[210:213], v199 offset:36864
	ds_read_b128 v[214:217], v199 offset:37888
	ds_read_b128 v[218:221], v199 offset:38912
	ds_read_b128 v[234:237], v199 offset:39936
	global_load_lds_dwordx4 v[246:247], off
	v_lshl_add_u64 v[246:247], s[14:15], 0, v[164:165]
	s_mov_b32 m0, s51
	s_nop 0
	global_load_lds_dwordx4 v[246:247], off
	s_waitcnt vmcnt(8)
	s_waitcnt lgkmcnt(0)
	s_barrier
	s_setprio 1
	s_waitcnt lgkmcnt(0)
	v_mfma_f32_16x16x32_bf16 v[140:143], v[48:51], v[186:189], v[140:143]
	v_mfma_f32_16x16x32_bf16 v[136:139], v[64:67], v[186:189], v[136:139]
	v_mfma_f32_16x16x32_bf16 v[124:127], v[48:51], v[202:205], v[124:127]
	v_mfma_f32_16x16x32_bf16 v[120:123], v[64:67], v[202:205], v[120:123]
	v_mfma_f32_16x16x32_bf16 v[108:111], v[48:51], v[210:213], v[108:111]
	v_mfma_f32_16x16x32_bf16 v[104:107], v[64:67], v[210:213], v[104:107]
	v_mfma_f32_16x16x32_bf16 v[92:95], v[48:51], v[218:221], v[92:95]
	v_mfma_f32_16x16x32_bf16 v[88:91], v[64:67], v[218:221], v[88:91]
	v_mfma_f32_16x16x32_bf16 v[140:143], v[52:55], v[190:193], v[140:143]
	v_mfma_f32_16x16x32_bf16 v[136:139], v[68:71], v[190:193], v[136:139]
	v_mfma_f32_16x16x32_bf16 v[124:127], v[52:55], v[206:209], v[124:127]
	v_mfma_f32_16x16x32_bf16 v[120:123], v[68:71], v[206:209], v[120:123]
	v_mfma_f32_16x16x32_bf16 v[108:111], v[52:55], v[214:217], v[108:111]
	v_mfma_f32_16x16x32_bf16 v[104:107], v[68:71], v[214:217], v[104:107]
	v_mfma_f32_16x16x32_bf16 v[92:95], v[52:55], v[234:237], v[92:95]
	v_mfma_f32_16x16x32_bf16 v[88:91], v[68:71], v[234:237], v[88:91]
	s_setprio 0
	s_setprio 1
	v_mfma_f32_16x16x32_bf16 v[132:135], v[144:147], v[186:189], v[132:135]
	v_mfma_f32_16x16x32_bf16 v[128:131], v[152:155], v[186:189], v[128:131]
	v_mfma_f32_16x16x32_bf16 v[116:119], v[144:147], v[202:205], v[116:119]
	v_mfma_f32_16x16x32_bf16 v[112:115], v[152:155], v[202:205], v[112:115]
	v_mfma_f32_16x16x32_bf16 v[100:103], v[144:147], v[210:213], v[100:103]
	v_mfma_f32_16x16x32_bf16 v[96:99], v[152:155], v[210:213], v[96:99]
	v_mfma_f32_16x16x32_bf16 v[84:87], v[144:147], v[218:221], v[84:87]
	v_mfma_f32_16x16x32_bf16 v[80:83], v[152:155], v[218:221], v[80:83]
	v_mfma_f32_16x16x32_bf16 v[132:135], v[148:151], v[190:193], v[132:135]
	v_mfma_f32_16x16x32_bf16 v[128:131], v[156:159], v[190:193], v[128:131]
	v_mfma_f32_16x16x32_bf16 v[116:119], v[148:151], v[206:209], v[116:119]
	v_mfma_f32_16x16x32_bf16 v[112:115], v[156:159], v[206:209], v[112:115]
	v_mfma_f32_16x16x32_bf16 v[100:103], v[148:151], v[214:217], v[100:103]
	v_mfma_f32_16x16x32_bf16 v[96:99], v[156:159], v[214:217], v[96:99]
	v_mfma_f32_16x16x32_bf16 v[84:87], v[148:151], v[234:237], v[84:87]
	v_mfma_f32_16x16x32_bf16 v[80:83], v[156:159], v[234:237], v[80:83]
	s_setprio 0
	s_barrier
; #define PG8_STAGE(bufoff, gbase, voff) do { _Pragma("unroll") for (int _i = 0; _i < 2; ++_i) \
;         __builtin_amdgcn_global_load_lds((const unsigned*)((const char*)(gbase) + (voff)[_i]), (PG8_LAS unsigned*)(lds + (bufoff) + ldsw + _i * 8192), 16, 0, 0); } while (0)
; #define PG8_LDA(dst, b, h) do { _Pragma("unroll") for (int m = 0; m < 4; ++m) _Pragma("unroll") for (int k = 0; k < 2; ++k) dst[m][k] = *(const PG8_LAS bf16x8*)(lds + PG8_SA(b, h) + aoff + m * 2048 + k * 1024); } while (0)
; #define PG8_MMA(ai, bj, At, Bt) do { __builtin_amdgcn_s_setprio(1); _Pragma("unroll") for (int m = 0; m < 4; ++m) _Pragma("unroll") for (int n = 0; n < 2; ++n) _Pragma("unroll") for (int k = 0; k < 2; ++k) \
;         acc[ai][bj][m][n] = __builtin_amdgcn_mfma_f32_16x16x32_bf16(Bt[n][k], At[m][k], acc[ai][bj][m][n], 0, 0, 0); __builtin_amdgcn_s_setprio(0); } while (0)
; #define PG8_WAIT_V(n) asm volatile("s_waitcnt vmcnt(" #n ")" ::: "memory")
; #define PG8_WAIT_L(n) asm volatile("s_waitcnt lgkmcnt(" #n ")" ::: "memory")
; #define PG8_BAR __builtin_amdgcn_s_barrier()
; #define PG8_SCHED __builtin_amdgcn_sched_barrier(0)
; template <class Epi, class Sched, bool ALIGN_EPI = false, bool SP2 = false>
; __device__ __forceinline__ void gemm_phase(PG8_LAS unsigned char* lds, const Gemm g, const Sched& S, const Epi& E) {
;     ...
;         for (int t = 0; t < nt; t += 2) {
;     ...
;             PG8_LDA(At, 1, 1); PG8_STAGE(PG8_SB(1, 0), b3, voffB); PG8_STAGE(PG8_SB(1, 1), b3 + hstep, voffB); PG8_STAGE(PG8_SA(1, 0), a3, voffA);
;             PG8_WAIT_V(8); PG8_WAIT_L(0); PG8_BAR; PG8_MMA(1, 0, At, B0); PG8_MMA(1, 1, At, B1); PG8_BAR; PG8_SCHED;
	s_add_i32 s14, s55, s44
	v_lshl_add_u64 v[194:195], v[194:195], 0, s[88:89]
	s_mov_b32 m0, s14
	ds_read_b128 v[186:189], v199 offset:49152
	ds_read_b128 v[190:193], v199 offset:50176
	ds_read_b128 v[202:205], v199 offset:51200
	ds_read_b128 v[206:209], v199 offset:52224
	ds_read_b128 v[210:213], v199 offset:53248
	ds_read_b128 v[214:217], v199 offset:54272
	ds_read_b128 v[218:221], v199 offset:55296
	ds_read_b128 v[234:237], v199 offset:56320
	global_load_lds_dwordx4 v[194:195], off
	s_add_i32 m0, s14, 0x2000
	s_add_u32 s4, s4, 0x40080
	v_lshl_add_u64 v[194:195], v[240:241], 0, s[88:89]
	s_addc_u32 s5, s5, 0
	s_add_i32 s14, s59, s44
	global_load_lds_dwordx4 v[194:195], off
	v_lshl_add_u64 v[194:195], s[4:5], 0, v[162:163]
	s_mov_b32 m0, s14
	s_nop 0
	global_load_lds_dwordx4 v[194:195], off
	v_lshl_add_u64 v[194:195], s[4:5], 0, v[166:167]
	s_add_i32 m0, s14, 0x2000
	s_nop 0
	global_load_lds_dwordx4 v[194:195], off
	v_lshl_add_u64 v[194:195], v[242:243], 0, s[88:89]
	s_mov_b32 m0, s96
	s_nop 0
	global_load_lds_dwordx4 v[194:195], off
	v_lshl_add_u64 v[194:195], v[244:245], 0, s[88:89]
	s_mov_b32 m0, s97
	s_nop 0
	global_load_lds_dwordx4 v[194:195], off
	s_waitcnt vmcnt(8)
	s_waitcnt lgkmcnt(0)
	s_barrier
	s_setprio 1
	s_waitcnt lgkmcnt(0)
	v_mfma_f32_16x16x32_bf16 v[76:79], v[48:51], v[186:189], v[76:79]
	v_mfma_f32_16x16x32_bf16 v[72:75], v[64:67], v[186:189], v[72:75]
	v_mfma_f32_16x16x32_bf16 v[60:63], v[48:51], v[202:205], v[60:63]
	v_mfma_f32_16x16x32_bf16 v[56:59], v[64:67], v[202:205], v[56:59]
	v_mfma_f32_16x16x32_bf16 v[28:31], v[48:51], v[210:213], v[28:31]
	v_mfma_f32_16x16x32_bf16 v[24:27], v[64:67], v[210:213], v[24:27]
	v_mfma_f32_16x16x32_bf16 v[12:15], v[48:51], v[218:221], v[12:15]
	v_mfma_f32_16x16x32_bf16 v[8:11], v[64:67], v[218:221], v[8:11]
	v_mfma_f32_16x16x32_bf16 v[76:79], v[52:55], v[190:193], v[76:79]
	v_mfma_f32_16x16x32_bf16 v[72:75], v[68:71], v[190:193], v[72:75]
	v_mfma_f32_16x16x32_bf16 v[60:63], v[52:55], v[206:209], v[60:63]
	v_mfma_f32_16x16x32_bf16 v[56:59], v[68:71], v[206:209], v[56:59]
	v_mfma_f32_16x16x32_bf16 v[28:31], v[52:55], v[214:217], v[28:31]
	v_mfma_f32_16x16x32_bf16 v[24:27], v[68:71], v[214:217], v[24:27]
	v_mfma_f32_16x16x32_bf16 v[12:15], v[52:55], v[234:237], v[12:15]
	v_mfma_f32_16x16x32_bf16 v[8:11], v[68:71], v[234:237], v[8:11]
	s_setprio 0
	s_setprio 1
	v_mfma_f32_16x16x32_bf16 v[32:35], v[144:147], v[186:189], v[32:35]
	v_mfma_f32_16x16x32_bf16 v[68:71], v[148:151], v[190:193], v[32:35]
	v_mfma_f32_16x16x32_bf16 v[32:35], v[152:155], v[186:189], v[36:39]
	v_mfma_f32_16x16x32_bf16 v[64:67], v[156:159], v[190:193], v[32:35]
	v_mfma_f32_16x16x32_bf16 v[32:35], v[144:147], v[202:205], v[40:43]
	v_mfma_f32_16x16x32_bf16 v[52:55], v[148:151], v[206:209], v[32:35]
	v_mfma_f32_16x16x32_bf16 v[32:35], v[152:155], v[202:205], v[44:47]
	v_mfma_f32_16x16x32_bf16 v[20:23], v[144:147], v[210:213], v[20:23]
	v_mfma_f32_16x16x32_bf16 v[16:19], v[152:155], v[210:213], v[16:19]
	v_mfma_f32_16x16x32_bf16 v[4:7], v[144:147], v[218:221], v[4:7]
	v_mfma_f32_16x16x32_bf16 v[0:3], v[152:155], v[218:221], v[0:3]
	v_mfma_f32_16x16x32_bf16 v[48:51], v[156:159], v[206:209], v[32:35]
	v_mfma_f32_16x16x32_bf16 v[20:23], v[148:151], v[214:217], v[20:23]
	v_mfma_f32_16x16x32_bf16 v[16:19], v[156:159], v[214:217], v[16:19]
	v_mfma_f32_16x16x32_bf16 v[4:7], v[148:151], v[234:237], v[4:7]
	v_mfma_f32_16x16x32_bf16 v[0:3], v[156:159], v[234:237], v[0:3]
	s_add_i32 s58, s58, 2
	s_add_u32 s56, s56, 0x100
	s_addc_u32 s57, s57, 0
	s_add_u32 s0, s0, 0x100
	s_addc_u32 s1, s1, 0
	s_cmp_gt_u32 s58, 13
	s_setprio 0
	s_barrier
	s_cbranch_scc0 .LBB0_212
	s_and_b64 vcc, exec, s[22:23]
	s_cbranch_vccz .LBB0_215
	s_barrier

; #define PG8_STAGE(bufoff, gbase, voff) do { _Pragma("unroll") for (int _i = 0; _i < 2; ++_i) \
;         __builtin_amdgcn_global_load_lds((const unsigned*)((const char*)(gbase) + (voff)[_i]), (PG8_LAS unsigned*)(lds + (bufoff) + ldsw + _i * 8192), 16, 0, 0); } while (0)
; #define PG8_LDA(dst, b, h) do { _Pragma("unroll") for (int m = 0; m < 4; ++m) _Pragma("unroll") for (int k = 0; k < 2; ++k) dst[m][k] = *(const PG8_LAS bf16x8*)(lds + PG8_SA(b, h) + aoff + m * 2048 + k * 1024); } while (0)
; #define PG8_LDB(dst, b, h) do { _Pragma("unroll") for (int n = 0; n < 2; ++n) _Pragma("unroll") for (int k = 0; k < 2; ++k) dst[n][k] = *(const PG8_LAS bf16x8*)(lds + PG8_SB(b, h) + boff + n * 2048 + k * 1024); } while (0)
; #define PG8_MMA(ai, bj, At, Bt) do { __builtin_amdgcn_s_setprio(1); _Pragma("unroll") for (int m = 0; m < 4; ++m) _Pragma("unroll") for (int n = 0; n < 2; ++n) _Pragma("unroll") for (int k = 0; k < 2; ++k) \
;         acc[ai][bj][m][n] = __builtin_amdgcn_mfma_f32_16x16x32_bf16(Bt[n][k], At[m][k], acc[ai][bj][m][n], 0, 0, 0); __builtin_amdgcn_s_setprio(0); } while (0)
; #define PG8_WAIT_V(n) asm volatile("s_waitcnt vmcnt(" #n ")" ::: "memory")
; #define PG8_WAIT_L(n) asm volatile("s_waitcnt lgkmcnt(" #n ")" ::: "memory")
; #define PG8_BAR __builtin_amdgcn_s_barrier()
; #define PG8_SCHED __builtin_amdgcn_sched_barrier(0)
; template <class Epi, class Sched, bool ALIGN_EPI = false, bool SP2 = false>
; __device__ __forceinline__ void gemm_phase(PG8_LAS unsigned char* lds, const Gemm g, const Sched& S, const Epi& E) {
;     ...
;             const bool last = (t == nt - 2);
;             const char* a1 = cA + (size_t)(t + 1) * kstep;
;             const char* a2 = last ? nA : cA + (size_t)(t + 2) * kstep; const char* b2 = last ? nB : cB + (size_t)(t + 2) * kstep;
;             const char* a3 = a2 + kstep; const char* b3 = b2 + kstep;
;             if (last && has_next) S.a_ready(nxt);
;             if constexpr (SP2) {
;             PG8_LDB(B0, 0, 0); PG8_LDB(B1, 0, 1); PG8_SCHED; PG8_LDA(At, 0, 0); PG8_STAGE(PG8_SA(1, 1), a1 + hstep, voffA);
;             PG8_WAIT_V(8); PG8_WAIT_L(0); PG8_BAR; PG8_MMA(0, 0, At, B0); PG8_MMA(0, 1, At, B1); PG8_BAR; PG8_SCHED;
;             PG8_LDA(At, 0, 1); PG8_STAGE(PG8_SB(0, 0), b2, voffB); PG8_STAGE(PG8_SB(0, 1), b2 + hstep, voffB); PG8_STAGE(PG8_SA(0, 0), a2, voffA);
.LBB0_316:
	s_add_u32 s14, s0, 0xfffc0080
	s_addc_u32 s15, s1, -1
	s_add_i32 s55, 0, 0x10000
	s_cmp_eq_u32 s59, 12
	s_cselect_b32 s31, s21, s15
	s_cselect_b32 s30, s54, s14
	s_cselect_b32 s15, s23, s58
	s_cselect_b32 s14, s56, s57
	s_add_i32 s62, 0, 0x14000
	s_waitcnt vmcnt(0) lgkmcnt(0)
	v_add_u32_e32 v52, s55, v171
	v_add_u32_e32 v166, s62, v171
	ds_read_b128 v[32:35], v52
	ds_read_b128 v[36:39], v52 offset:1024
	ds_read_b128 v[48:51], v52 offset:2048
	ds_read_b128 v[52:55], v52 offset:3072
	ds_read_b128 v[158:161], v166
	ds_read_b128 v[162:165], v166 offset:1024
	ds_read_b128 v[182:185], v166 offset:2048
	ds_read_b128 v[186:189], v166 offset:3072
	v_lshl_add_u64 v[166:167], s[0:1], 0, v[156:157]
	s_add_i32 m0, s39, 0xc000
	ds_read_b128 v[190:193], v174
	ds_read_b128 v[194:197], v174 offset:1024
	ds_read_b128 v[198:201], v174 offset:2048
	ds_read_b128 v[202:205], v174 offset:3072
	ds_read_b128 v[206:209], v174 offset:4096
	ds_read_b128 v[210:213], v174 offset:5120
	ds_read_b128 v[214:217], v174 offset:6144
	ds_read_b128 v[218:221], v174 offset:7168
	global_load_lds_dwordx4 v[166:167], off
	v_lshl_add_u64 v[166:167], s[0:1], 0, v[154:155]
	s_add_i32 m0, s39, 0xe000
	s_nop 0
	global_load_lds_dwordx4 v[166:167], off
	s_waitcnt vmcnt(8)
	s_waitcnt lgkmcnt(0)
	s_barrier
	s_setprio 1
	s_waitcnt lgkmcnt(0)
	v_mfma_f32_16x16x32_bf16 v[140:143], v[32:35], v[190:193], v[140:143]
	v_mfma_f32_16x16x32_bf16 v[136:139], v[48:51], v[190:193], v[136:139]
	v_mfma_f32_16x16x32_bf16 v[124:127], v[32:35], v[198:201], v[124:127]
	v_mfma_f32_16x16x32_bf16 v[120:123], v[48:51], v[198:201], v[120:123]
	v_mfma_f32_16x16x32_bf16 v[108:111], v[32:35], v[206:209], v[108:111]
	v_mfma_f32_16x16x32_bf16 v[104:107], v[48:51], v[206:209], v[104:107]
	v_mfma_f32_16x16x32_bf16 v[92:95], v[32:35], v[214:217], v[92:95]
	v_mfma_f32_16x16x32_bf16 v[88:91], v[48:51], v[214:217], v[88:91]
	v_mfma_f32_16x16x32_bf16 v[140:143], v[36:39], v[194:197], v[140:143]
	v_mfma_f32_16x16x32_bf16 v[136:139], v[52:55], v[194:197], v[136:139]
	v_mfma_f32_16x16x32_bf16 v[124:127], v[36:39], v[202:205], v[124:127]
	v_mfma_f32_16x16x32_bf16 v[120:123], v[52:55], v[202:205], v[120:123]
	v_mfma_f32_16x16x32_bf16 v[108:111], v[36:39], v[210:213], v[108:111]
	v_mfma_f32_16x16x32_bf16 v[104:107], v[52:55], v[210:213], v[104:107]
	v_mfma_f32_16x16x32_bf16 v[92:95], v[36:39], v[218:221], v[92:95]
	v_mfma_f32_16x16x32_bf16 v[88:91], v[52:55], v[218:221], v[88:91]
	s_setprio 0
	s_setprio 1
	v_mfma_f32_16x16x32_bf16 v[132:135], v[158:161], v[190:193], v[132:135]
	v_mfma_f32_16x16x32_bf16 v[128:131], v[182:185], v[190:193], v[128:131]
	v_mfma_f32_16x16x32_bf16 v[116:119], v[158:161], v[198:201], v[116:119]
	v_mfma_f32_16x16x32_bf16 v[112:115], v[182:185], v[198:201], v[112:115]
	v_mfma_f32_16x16x32_bf16 v[100:103], v[158:161], v[206:209], v[100:103]
	v_mfma_f32_16x16x32_bf16 v[96:99], v[182:185], v[206:209], v[96:99]
	v_mfma_f32_16x16x32_bf16 v[84:87], v[158:161], v[214:217], v[84:87]
	v_mfma_f32_16x16x32_bf16 v[80:83], v[182:185], v[214:217], v[80:83]
	v_mfma_f32_16x16x32_bf16 v[132:135], v[162:165], v[194:197], v[132:135]
	v_mfma_f32_16x16x32_bf16 v[128:131], v[186:189], v[194:197], v[128:131]
	v_mfma_f32_16x16x32_bf16 v[116:119], v[162:165], v[202:205], v[116:119]
	v_mfma_f32_16x16x32_bf16 v[112:115], v[186:189], v[202:205], v[112:115]
	v_mfma_f32_16x16x32_bf16 v[100:103], v[162:165], v[210:213], v[100:103]
	v_mfma_f32_16x16x32_bf16 v[96:99], v[186:189], v[210:213], v[96:99]
	v_mfma_f32_16x16x32_bf16 v[84:87], v[162:165], v[218:221], v[84:87]
	v_mfma_f32_16x16x32_bf16 v[80:83], v[186:189], v[218:221], v[80:83]
	s_setprio 0
	s_barrier
	s_add_i32 s55, s55, s38
	v_lshl_add_u64 v[166:167], s[14:15], 0, v[148:149]
	s_mov_b32 m0, s55
	ds_read_b128 v[190:193], v174 offset:16384
	ds_read_b128 v[194:197], v174 offset:17408
	ds_read_b128 v[198:201], v174 offset:18432
	ds_read_b128 v[202:205], v174 offset:19456
	ds_read_b128 v[206:209], v174 offset:20480
	ds_read_b128 v[210:213], v174 offset:21504
	ds_read_b128 v[214:217], v174 offset:22528
	ds_read_b128 v[218:221], v174 offset:23552
	global_load_lds_dwordx4 v[166:167], off
	s_add_i32 m0, s55, 0x2000
	s_add_u32 s60, s14, 0x40000
	v_lshl_add_u64 v[234:235], s[14:15], 0, v[144:145]
	s_addc_u32 s61, s15, 0
	s_add_i32 s55, s62, s38
	global_load_lds_dwordx4 v[234:235], off
	v_lshl_add_u64 v[236:237], s[60:61], 0, v[148:149]
	s_mov_b32 m0, s55
	v_lshl_add_u64 v[240:241], s[30:31], 0, v[146:147]
	global_load_lds_dwordx4 v[236:237], off
	v_lshl_add_u64 v[236:237], s[60:61], 0, v[144:145]
	s_add_i32 m0, s55, 0x2000
	s_nop 0
	global_load_lds_dwordx4 v[236:237], off
	v_lshl_add_u64 v[236:237], s[30:31], 0, v[150:151]
	s_mov_b32 m0, s39
	s_nop 0
	global_load_lds_dwordx4 v[236:237], off
	s_mov_b32 m0, s40
	s_nop 0
	global_load_lds_dwordx4 v[240:241], off
	s_waitcnt vmcnt(8)
	s_waitcnt lgkmcnt(0)
	s_barrier
; #define PG8_STAGE(bufoff, gbase, voff) do { _Pragma("unroll") for (int _i = 0; _i < 2; ++_i) \
;         __builtin_amdgcn_global_load_lds((const unsigned*)((const char*)(gbase) + (voff)[_i]), (PG8_LAS unsigned*)(lds + (bufoff) + ldsw + _i * 8192), 16, 0, 0); } while (0)
; #define PG8_LDA(dst, b, h) do { _Pragma("unroll") for (int m = 0; m < 4; ++m) _Pragma("unroll") for (int k = 0; k < 2; ++k) dst[m][k] = *(const PG8_LAS bf16x8*)(lds + PG8_SA(b, h) + aoff + m * 2048 + k * 1024); } while (0)
; #define PG8_LDB(dst, b, h) do { _Pragma("unroll") for (int n = 0; n < 2; ++n) _Pragma("unroll") for (int k = 0; k < 2; ++k) dst[n][k] = *(const PG8_LAS bf16x8*)(lds + PG8_SB(b, h) + boff + n * 2048 + k * 1024); } while (0)
; #define PG8_MMA(ai, bj, At, Bt) do { __builtin_amdgcn_s_setprio(1); _Pragma("unroll") for (int m = 0; m < 4; ++m) _Pragma("unroll") for (int n = 0; n < 2; ++n) _Pragma("unroll") for (int k = 0; k < 2; ++k) \
;         acc[ai][bj][m][n] = __builtin_amdgcn_mfma_f32_16x16x32_bf16(Bt[n][k], At[m][k], acc[ai][bj][m][n], 0, 0, 0); __builtin_amdgcn_s_setprio(0); } while (0)
; #define PG8_WAIT_V(n) asm volatile("s_waitcnt vmcnt(" #n ")" ::: "memory")
; #define PG8_WAIT_L(n) asm volatile("s_waitcnt lgkmcnt(" #n ")" ::: "memory")
; #define PG8_BAR __builtin_amdgcn_s_barrier()
; #define PG8_SCHED __builtin_amdgcn_sched_barrier(0)
; template <class Epi, class Sched, bool ALIGN_EPI = false, bool SP2 = false>
; __device__ __forceinline__ void gemm_phase(PG8_LAS unsigned char* lds, const Gemm g, const Sched& S, const Epi& E) {
;     ...
;             PG8_WAIT_V(8); PG8_WAIT_L(0); PG8_BAR; PG8_MMA(1, 0, At, B0); PG8_MMA(1, 1, At, B1); PG8_BAR; PG8_SCHED;
;             PG8_LDB(B0, 1, 0); PG8_LDB(B1, 1, 1); PG8_SCHED; PG8_LDA(At, 1, 0); PG8_STAGE(PG8_SA(0, 1), a2 + hstep, voffA);
;             PG8_WAIT_V(8); PG8_WAIT_L(0); PG8_BAR; PG8_MMA(0, 0, At, B0); PG8_MMA(0, 1, At, B1); PG8_BAR; PG8_SCHED;
	s_setprio 1
	s_waitcnt lgkmcnt(0)
	v_mfma_f32_16x16x32_bf16 v[76:79], v[32:35], v[190:193], v[76:79]
	v_mfma_f32_16x16x32_bf16 v[72:75], v[48:51], v[190:193], v[72:75]
	v_mfma_f32_16x16x32_bf16 v[60:63], v[32:35], v[198:201], v[60:63]
	v_mfma_f32_16x16x32_bf16 v[56:59], v[48:51], v[198:201], v[56:59]
	v_mfma_f32_16x16x32_bf16 v[28:31], v[32:35], v[206:209], v[28:31]
	v_mfma_f32_16x16x32_bf16 v[24:27], v[48:51], v[206:209], v[24:27]
	v_mfma_f32_16x16x32_bf16 v[12:15], v[32:35], v[214:217], v[12:15]
	v_mfma_f32_16x16x32_bf16 v[8:11], v[48:51], v[214:217], v[8:11]
	v_mfma_f32_16x16x32_bf16 v[76:79], v[36:39], v[194:197], v[76:79]
	v_mfma_f32_16x16x32_bf16 v[72:75], v[52:55], v[194:197], v[72:75]
	v_mfma_f32_16x16x32_bf16 v[60:63], v[36:39], v[202:205], v[60:63]
	v_mfma_f32_16x16x32_bf16 v[56:59], v[52:55], v[202:205], v[56:59]
	v_mfma_f32_16x16x32_bf16 v[28:31], v[36:39], v[210:213], v[28:31]
	v_mfma_f32_16x16x32_bf16 v[24:27], v[52:55], v[210:213], v[24:27]
	v_mfma_f32_16x16x32_bf16 v[12:15], v[36:39], v[218:221], v[12:15]
	v_mfma_f32_16x16x32_bf16 v[8:11], v[52:55], v[218:221], v[8:11]
	s_setprio 0
	s_setprio 1
	v_mfma_f32_16x16x32_bf16 v[44:47], v[158:161], v[198:201], v[44:47]
	v_mfma_f32_16x16x32_bf16 v[40:43], v[182:185], v[198:201], v[40:43]
	v_mfma_f32_16x16x32_bf16 v[20:23], v[158:161], v[206:209], v[20:23]
	v_mfma_f32_16x16x32_bf16 v[16:19], v[182:185], v[206:209], v[16:19]
	v_mfma_f32_16x16x32_bf16 v[4:7], v[158:161], v[214:217], v[4:7]
	v_mfma_f32_16x16x32_bf16 v[0:3], v[182:185], v[214:217], v[0:3]
	v_mfma_f32_16x16x32_bf16 v[32:35], v[158:161], v[190:193], v[68:71]
	v_mfma_f32_16x16x32_bf16 v[36:39], v[182:185], v[190:193], v[64:67]
	v_mfma_f32_16x16x32_bf16 v[44:47], v[162:165], v[202:205], v[44:47]
	v_mfma_f32_16x16x32_bf16 v[40:43], v[186:189], v[202:205], v[40:43]
	v_mfma_f32_16x16x32_bf16 v[20:23], v[162:165], v[210:213], v[20:23]
	v_mfma_f32_16x16x32_bf16 v[16:19], v[186:189], v[210:213], v[16:19]
	v_mfma_f32_16x16x32_bf16 v[4:7], v[162:165], v[218:221], v[4:7]
	v_mfma_f32_16x16x32_bf16 v[0:3], v[186:189], v[218:221], v[0:3]
	v_mfma_f32_16x16x32_bf16 v[32:35], v[162:165], v[194:197], v[32:35]
	v_mfma_f32_16x16x32_bf16 v[36:39], v[186:189], v[194:197], v[36:39]
	s_setprio 0
	s_barrier
	s_add_i32 s55, 0, 0x18000
	s_add_i32 s60, 0, 0x1c000
	v_add_u32_e32 v68, s55, v171
	v_add_u32_e32 v175, s60, v171
	ds_read_b128 v[48:51], v68
	ds_read_b128 v[52:55], v68 offset:1024
	ds_read_b128 v[64:67], v68 offset:2048
	ds_read_b128 v[68:71], v68 offset:3072
	ds_read_b128 v[158:161], v175
	ds_read_b128 v[162:165], v175 offset:1024
	ds_read_b128 v[182:185], v175 offset:2048
	ds_read_b128 v[186:189], v175 offset:3072
	s_add_u32 s30, s30, 0x40000
	s_addc_u32 s31, s31, 0
	s_mov_b32 m0, s41
	v_lshl_add_u64 v[242:243], s[30:31], 0, v[150:151]
	ds_read_b128 v[190:193], v174 offset:32768
	ds_read_b128 v[194:197], v174 offset:33792
	ds_read_b128 v[198:201], v174 offset:34816
	ds_read_b128 v[202:205], v174 offset:35840
	ds_read_b128 v[206:209], v174 offset:36864
	ds_read_b128 v[210:213], v174 offset:37888
	ds_read_b128 v[214:217], v174 offset:38912
	ds_read_b128 v[218:221], v174 offset:39936
	global_load_lds_dwordx4 v[242:243], off
	v_lshl_add_u64 v[242:243], s[30:31], 0, v[146:147]
	s_mov_b32 m0, s42
	s_nop 0
	global_load_lds_dwordx4 v[242:243], off
	s_waitcnt vmcnt(8)
	s_waitcnt lgkmcnt(0)
	s_barrier
	s_setprio 1
	s_waitcnt lgkmcnt(0)
	v_mfma_f32_16x16x32_bf16 v[140:143], v[48:51], v[190:193], v[140:143]
	v_mfma_f32_16x16x32_bf16 v[136:139], v[64:67], v[190:193], v[136:139]
	v_mfma_f32_16x16x32_bf16 v[124:127], v[48:51], v[198:201], v[124:127]
	v_mfma_f32_16x16x32_bf16 v[120:123], v[64:67], v[198:201], v[120:123]
	v_mfma_f32_16x16x32_bf16 v[108:111], v[48:51], v[206:209], v[108:111]
	v_mfma_f32_16x16x32_bf16 v[104:107], v[64:67], v[206:209], v[104:107]
	v_mfma_f32_16x16x32_bf16 v[92:95], v[48:51], v[214:217], v[92:95]
	v_mfma_f32_16x16x32_bf16 v[88:91], v[64:67], v[214:217], v[88:91]
	v_mfma_f32_16x16x32_bf16 v[140:143], v[52:55], v[194:197], v[140:143]
	v_mfma_f32_16x16x32_bf16 v[136:139], v[68:71], v[194:197], v[136:139]
	v_mfma_f32_16x16x32_bf16 v[124:127], v[52:55], v[202:205], v[124:127]
	v_mfma_f32_16x16x32_bf16 v[120:123], v[68:71], v[202:205], v[120:123]
	v_mfma_f32_16x16x32_bf16 v[108:111], v[52:55], v[210:213], v[108:111]
	v_mfma_f32_16x16x32_bf16 v[104:107], v[68:71], v[210:213], v[104:107]
	v_mfma_f32_16x16x32_bf16 v[92:95], v[52:55], v[218:221], v[92:95]
	v_mfma_f32_16x16x32_bf16 v[88:91], v[68:71], v[218:221], v[88:91]
	s_setprio 0
	s_setprio 1
	v_mfma_f32_16x16x32_bf16 v[132:135], v[158:161], v[190:193], v[132:135]
	v_mfma_f32_16x16x32_bf16 v[128:131], v[182:185], v[190:193], v[128:131]
	v_mfma_f32_16x16x32_bf16 v[116:119], v[158:161], v[198:201], v[116:119]
	v_mfma_f32_16x16x32_bf16 v[112:115], v[182:185], v[198:201], v[112:115]
	v_mfma_f32_16x16x32_bf16 v[100:103], v[158:161], v[206:209], v[100:103]
	v_mfma_f32_16x16x32_bf16 v[96:99], v[182:185], v[206:209], v[96:99]
	v_mfma_f32_16x16x32_bf16 v[84:87], v[158:161], v[214:217], v[84:87]
	v_mfma_f32_16x16x32_bf16 v[80:83], v[182:185], v[214:217], v[80:83]
	v_mfma_f32_16x16x32_bf16 v[132:135], v[162:165], v[194:197], v[132:135]
	v_mfma_f32_16x16x32_bf16 v[128:131], v[186:189], v[194:197], v[128:131]
	v_mfma_f32_16x16x32_bf16 v[116:119], v[162:165], v[202:205], v[116:119]
	v_mfma_f32_16x16x32_bf16 v[112:115], v[186:189], v[202:205], v[112:115]
	v_mfma_f32_16x16x32_bf16 v[100:103], v[162:165], v[210:213], v[100:103]
	v_mfma_f32_16x16x32_bf16 v[96:99], v[186:189], v[210:213], v[96:99]
	v_mfma_f32_16x16x32_bf16 v[84:87], v[162:165], v[218:221], v[84:87]
	v_mfma_f32_16x16x32_bf16 v[80:83], v[186:189], v[218:221], v[80:83]
	s_setprio 0
	s_barrier
; #define PG8_STAGE(bufoff, gbase, voff) do { _Pragma("unroll") for (int _i = 0; _i < 2; ++_i) \
;         __builtin_amdgcn_global_load_lds((const unsigned*)((const char*)(gbase) + (voff)[_i]), (PG8_LAS unsigned*)(lds + (bufoff) + ldsw + _i * 8192), 16, 0, 0); } while (0)
; #define PG8_LDA(dst, b, h) do { _Pragma("unroll") for (int m = 0; m < 4; ++m) _Pragma("unroll") for (int k = 0; k < 2; ++k) dst[m][k] = *(const PG8_LAS bf16x8*)(lds + PG8_SA(b, h) + aoff + m * 2048 + k * 1024); } while (0)
; #define PG8_MMA(ai, bj, At, Bt) do { __builtin_amdgcn_s_setprio(1); _Pragma("unroll") for (int m = 0; m < 4; ++m) _Pragma("unroll") for (int n = 0; n < 2; ++n) _Pragma("unroll") for (int k = 0; k < 2; ++k) \
;         acc[ai][bj][m][n] = __builtin_amdgcn_mfma_f32_16x16x32_bf16(Bt[n][k], At[m][k], acc[ai][bj][m][n], 0, 0, 0); __builtin_amdgcn_s_setprio(0); } while (0)
; #define PG8_WAIT_V(n) asm volatile("s_waitcnt vmcnt(" #n ")" ::: "memory")
; #define PG8_WAIT_L(n) asm volatile("s_waitcnt lgkmcnt(" #n ")" ::: "memory")
; #define PG8_BAR __builtin_amdgcn_s_barrier()
; #define PG8_SCHED __builtin_amdgcn_sched_barrier(0)
; template <class Epi, class Sched, bool ALIGN_EPI = false, bool SP2 = false>
; __device__ __forceinline__ void gemm_phase(PG8_LAS unsigned char* lds, const Gemm g, const Sched& S, const Epi& E) {
;     ...
;         for (int t = 0; t < nt; t += 2) {
;     ...
;             PG8_LDA(At, 1, 1); PG8_STAGE(PG8_SB(1, 0), b3, voffB); PG8_STAGE(PG8_SB(1, 1), b3 + hstep, voffB); PG8_STAGE(PG8_SA(1, 0), a3, voffA);
;             PG8_WAIT_V(8); PG8_WAIT_L(0); PG8_BAR; PG8_MMA(1, 0, At, B0); PG8_MMA(1, 1, At, B1); PG8_BAR; PG8_SCHED;
	s_add_i32 s30, s55, s38
	v_lshl_add_u64 v[166:167], v[166:167], 0, s[88:89]
	s_mov_b32 m0, s30
	ds_read_b128 v[190:193], v174 offset:49152
	ds_read_b128 v[194:197], v174 offset:50176
	ds_read_b128 v[198:201], v174 offset:51200
	ds_read_b128 v[202:205], v174 offset:52224
	ds_read_b128 v[206:209], v174 offset:53248
	ds_read_b128 v[210:213], v174 offset:54272
	ds_read_b128 v[214:217], v174 offset:55296
	ds_read_b128 v[218:221], v174 offset:56320
	global_load_lds_dwordx4 v[166:167], off
	s_add_i32 m0, s30, 0x2000
	s_add_u32 s14, s14, 0x40080
	v_lshl_add_u64 v[166:167], v[234:235], 0, s[88:89]
	s_addc_u32 s15, s15, 0
	s_add_i32 s30, s60, s38
	global_load_lds_dwordx4 v[166:167], off
	v_lshl_add_u64 v[166:167], s[14:15], 0, v[148:149]
	s_mov_b32 m0, s30
	s_nop 0
	global_load_lds_dwordx4 v[166:167], off
	v_lshl_add_u64 v[166:167], s[14:15], 0, v[144:145]
	s_add_i32 m0, s30, 0x2000
	s_nop 0
	global_load_lds_dwordx4 v[166:167], off
	v_lshl_add_u64 v[166:167], v[236:237], 0, s[88:89]
	s_mov_b32 m0, s52
	s_nop 0
	global_load_lds_dwordx4 v[166:167], off
	v_lshl_add_u64 v[166:167], v[240:241], 0, s[88:89]
	s_mov_b32 m0, s53
	s_nop 0
	global_load_lds_dwordx4 v[166:167], off
	s_waitcnt vmcnt(8)
	s_waitcnt lgkmcnt(0)
	s_barrier
	s_setprio 1
	s_waitcnt lgkmcnt(0)
	v_mfma_f32_16x16x32_bf16 v[76:79], v[48:51], v[190:193], v[76:79]
	v_mfma_f32_16x16x32_bf16 v[72:75], v[64:67], v[190:193], v[72:75]
	v_mfma_f32_16x16x32_bf16 v[60:63], v[48:51], v[198:201], v[60:63]
	v_mfma_f32_16x16x32_bf16 v[56:59], v[64:67], v[198:201], v[56:59]
	v_mfma_f32_16x16x32_bf16 v[28:31], v[48:51], v[206:209], v[28:31]
	v_mfma_f32_16x16x32_bf16 v[24:27], v[64:67], v[206:209], v[24:27]
	v_mfma_f32_16x16x32_bf16 v[12:15], v[48:51], v[214:217], v[12:15]
	v_mfma_f32_16x16x32_bf16 v[8:11], v[64:67], v[214:217], v[8:11]
	v_mfma_f32_16x16x32_bf16 v[76:79], v[52:55], v[194:197], v[76:79]
	v_mfma_f32_16x16x32_bf16 v[72:75], v[68:71], v[194:197], v[72:75]
	v_mfma_f32_16x16x32_bf16 v[60:63], v[52:55], v[202:205], v[60:63]
	v_mfma_f32_16x16x32_bf16 v[56:59], v[68:71], v[202:205], v[56:59]
	v_mfma_f32_16x16x32_bf16 v[28:31], v[52:55], v[210:213], v[28:31]
	v_mfma_f32_16x16x32_bf16 v[24:27], v[68:71], v[210:213], v[24:27]
	v_mfma_f32_16x16x32_bf16 v[12:15], v[52:55], v[218:221], v[12:15]
	v_mfma_f32_16x16x32_bf16 v[8:11], v[68:71], v[218:221], v[8:11]
	s_setprio 0
	s_setprio 1
	v_mfma_f32_16x16x32_bf16 v[32:35], v[158:161], v[190:193], v[32:35]
	v_mfma_f32_16x16x32_bf16 v[68:71], v[162:165], v[194:197], v[32:35]
	v_mfma_f32_16x16x32_bf16 v[32:35], v[182:185], v[190:193], v[36:39]
	v_mfma_f32_16x16x32_bf16 v[64:67], v[186:189], v[194:197], v[32:35]
	v_mfma_f32_16x16x32_bf16 v[32:35], v[158:161], v[198:201], v[44:47]
	v_mfma_f32_16x16x32_bf16 v[44:47], v[162:165], v[202:205], v[32:35]
	v_mfma_f32_16x16x32_bf16 v[32:35], v[182:185], v[198:201], v[40:43]
	v_mfma_f32_16x16x32_bf16 v[20:23], v[158:161], v[206:209], v[20:23]
	v_mfma_f32_16x16x32_bf16 v[16:19], v[182:185], v[206:209], v[16:19]
	v_mfma_f32_16x16x32_bf16 v[4:7], v[158:161], v[214:217], v[4:7]
	v_mfma_f32_16x16x32_bf16 v[0:3], v[182:185], v[214:217], v[0:3]
	v_mfma_f32_16x16x32_bf16 v[40:43], v[186:189], v[202:205], v[32:35]
	v_mfma_f32_16x16x32_bf16 v[20:23], v[162:165], v[210:213], v[20:23]
	v_mfma_f32_16x16x32_bf16 v[16:19], v[186:189], v[210:213], v[16:19]
	v_mfma_f32_16x16x32_bf16 v[4:7], v[162:165], v[218:221], v[4:7]
	v_mfma_f32_16x16x32_bf16 v[0:3], v[186:189], v[218:221], v[0:3]
	s_add_i32 s59, s59, 2
	s_add_u32 s57, s57, 0x100
	s_addc_u32 s58, s58, 0
	s_add_u32 s0, s0, 0x100
	s_addc_u32 s1, s1, 0
	s_cmp_gt_u32 s59, 13
	s_setprio 0
	s_barrier
	s_cbranch_scc0 .LBB0_316
	s_and_b64 vcc, exec, s[18:19]
	s_cbranch_vccz .LBB0_319
	s_barrier

; #define PG8_STAGE(bufoff, gbase, voff) do { _Pragma("unroll") for (int _i = 0; _i < 2; ++_i) \
;         __builtin_amdgcn_global_load_lds((const unsigned*)((const char*)(gbase) + (voff)[_i]), (PG8_LAS unsigned*)(lds + (bufoff) + ldsw + _i * 8192), 16, 0, 0); } while (0)
; #define PG8_LDA(dst, b, h) do { _Pragma("unroll") for (int m = 0; m < 4; ++m) _Pragma("unroll") for (int k = 0; k < 2; ++k) dst[m][k] = *(const PG8_LAS bf16x8*)(lds + PG8_SA(b, h) + aoff + m * 2048 + k * 1024); } while (0)
; #define PG8_LDB(dst, b, h) do { _Pragma("unroll") for (int n = 0; n < 2; ++n) _Pragma("unroll") for (int k = 0; k < 2; ++k) dst[n][k] = *(const PG8_LAS bf16x8*)(lds + PG8_SB(b, h) + boff + n * 2048 + k * 1024); } while (0)
; #define PG8_MMA(ai, bj, At, Bt) do { __builtin_amdgcn_s_setprio(1); _Pragma("unroll") for (int m = 0; m < 4; ++m) _Pragma("unroll") for (int n = 0; n < 2; ++n) _Pragma("unroll") for (int k = 0; k < 2; ++k) \
;         acc[ai][bj][m][n] = __builtin_amdgcn_mfma_f32_16x16x32_bf16(Bt[n][k], At[m][k], acc[ai][bj][m][n], 0, 0, 0); __builtin_amdgcn_s_setprio(0); } while (0)
; #define PG8_WAIT_V(n) asm volatile("s_waitcnt vmcnt(" #n ")" ::: "memory")
; #define PG8_WAIT_L(n) asm volatile("s_waitcnt lgkmcnt(" #n ")" ::: "memory")
; #define PG8_BAR __builtin_amdgcn_s_barrier()
; #define PG8_SCHED __builtin_amdgcn_sched_barrier(0)
; template <class Epi, class Sched, bool ALIGN_EPI = false, bool SP2 = false>
; __device__ __forceinline__ void gemm_phase(PG8_LAS unsigned char* lds, const Gemm g, const Sched& S, const Epi& E) {
;     ...
;             const bool last = (t == nt - 2);
;             const char* a1 = cA + (size_t)(t + 1) * kstep;
;             const char* a2 = last ? nA : cA + (size_t)(t + 2) * kstep; const char* b2 = last ? nB : cB + (size_t)(t + 2) * kstep;
;             const char* a3 = a2 + kstep; const char* b3 = b2 + kstep;
;             if (last && has_next) S.a_ready(nxt);
;             if constexpr (SP2) {
;             PG8_LDB(B0, 0, 0); PG8_LDB(B1, 0, 1); PG8_SCHED; PG8_LDA(At, 0, 0); PG8_STAGE(PG8_SA(1, 1), a1 + hstep, voffA);
;             PG8_WAIT_V(8); PG8_WAIT_L(0); PG8_BAR; PG8_MMA(0, 0, At, B0); PG8_MMA(0, 1, At, B1); PG8_BAR; PG8_SCHED;
;             PG8_LDA(At, 0, 1); PG8_STAGE(PG8_SB(0, 0), b2, voffB); PG8_STAGE(PG8_SB(0, 1), b2 + hstep, voffB); PG8_STAGE(PG8_SA(0, 0), a2, voffA);
.LBB0_910:
	s_add_u32 s10, s8, 0xfffc0080
	s_addc_u32 s11, s9, -1
	s_add_i32 s55, 0, 0x10000
	s_cmp_eq_u32 s69, 12
	s_cselect_b32 s13, s15, s11
	s_cselect_b32 s12, s57, s10
	s_cselect_b32 s11, s43, s68
	s_cselect_b32 s10, s58, s59
	s_add_i32 s70, 0, 0x14000
	v_add_u32_e32 v68, s55, v235
	v_add_u32_e32 v156, s70, v235
	ds_read_b128 v[48:51], v68
	ds_read_b128 v[56:59], v68 offset:1024
	ds_read_b128 v[64:67], v68 offset:2048
	ds_read_b128 v[68:71], v68 offset:3072
	ds_read_b128 v[144:147], v156
	ds_read_b128 v[148:151], v156 offset:1024
	ds_read_b128 v[152:155], v156 offset:2048
	ds_read_b128 v[156:159], v156 offset:3072
	v_lshl_add_u64 v[208:209], s[8:9], 0, v[190:191]
	s_add_i32 m0, s65, 0xc000
	ds_read_b128 v[160:163], v237
	ds_read_b128 v[164:167], v237 offset:1024
	ds_read_b128 v[168:171], v237 offset:2048
	ds_read_b128 v[172:175], v237 offset:3072
	ds_read_b128 v[192:195], v237 offset:4096
	ds_read_b128 v[196:199], v237 offset:5120
	ds_read_b128 v[200:203], v237 offset:6144
	ds_read_b128 v[204:207], v237 offset:7168
	global_load_lds_dwordx4 v[208:209], off
	v_lshl_add_u64 v[208:209], s[8:9], 0, v[188:189]
	s_add_i32 m0, s65, 0xe000
	s_nop 0
	global_load_lds_dwordx4 v[208:209], off
	s_waitcnt vmcnt(8)
	s_waitcnt lgkmcnt(0)
	s_barrier
	s_setprio 1
	s_waitcnt lgkmcnt(0)
	v_mfma_f32_16x16x32_bf16 v[140:143], v[48:51], v[160:163], v[140:143]
	v_mfma_f32_16x16x32_bf16 v[136:139], v[64:67], v[160:163], v[136:139]
	v_mfma_f32_16x16x32_bf16 v[124:127], v[48:51], v[168:171], v[124:127]
	v_mfma_f32_16x16x32_bf16 v[120:123], v[64:67], v[168:171], v[120:123]
	v_mfma_f32_16x16x32_bf16 v[108:111], v[48:51], v[192:195], v[108:111]
	v_mfma_f32_16x16x32_bf16 v[104:107], v[64:67], v[192:195], v[104:107]
	v_mfma_f32_16x16x32_bf16 v[92:95], v[48:51], v[200:203], v[92:95]
	v_mfma_f32_16x16x32_bf16 v[88:91], v[64:67], v[200:203], v[88:91]
	v_mfma_f32_16x16x32_bf16 v[140:143], v[56:59], v[164:167], v[140:143]
	v_mfma_f32_16x16x32_bf16 v[136:139], v[68:71], v[164:167], v[136:139]
	v_mfma_f32_16x16x32_bf16 v[124:127], v[56:59], v[172:175], v[124:127]
	v_mfma_f32_16x16x32_bf16 v[120:123], v[68:71], v[172:175], v[120:123]
	v_mfma_f32_16x16x32_bf16 v[108:111], v[56:59], v[196:199], v[108:111]
	v_mfma_f32_16x16x32_bf16 v[104:107], v[68:71], v[196:199], v[104:107]
	v_mfma_f32_16x16x32_bf16 v[92:95], v[56:59], v[204:207], v[92:95]
	v_mfma_f32_16x16x32_bf16 v[88:91], v[68:71], v[204:207], v[88:91]
	s_setprio 0
	s_setprio 1
	v_mfma_f32_16x16x32_bf16 v[132:135], v[144:147], v[160:163], v[132:135]
	v_mfma_f32_16x16x32_bf16 v[128:131], v[152:155], v[160:163], v[128:131]
	v_mfma_f32_16x16x32_bf16 v[116:119], v[144:147], v[168:171], v[116:119]
	v_mfma_f32_16x16x32_bf16 v[112:115], v[152:155], v[168:171], v[112:115]
	v_mfma_f32_16x16x32_bf16 v[100:103], v[144:147], v[192:195], v[100:103]
	v_mfma_f32_16x16x32_bf16 v[96:99], v[152:155], v[192:195], v[96:99]
	v_mfma_f32_16x16x32_bf16 v[84:87], v[144:147], v[200:203], v[84:87]
	v_mfma_f32_16x16x32_bf16 v[80:83], v[152:155], v[200:203], v[80:83]
	v_mfma_f32_16x16x32_bf16 v[132:135], v[148:151], v[164:167], v[132:135]
	v_mfma_f32_16x16x32_bf16 v[128:131], v[156:159], v[164:167], v[128:131]
	v_mfma_f32_16x16x32_bf16 v[116:119], v[148:151], v[172:175], v[116:119]
	v_mfma_f32_16x16x32_bf16 v[112:115], v[156:159], v[172:175], v[112:115]
	v_mfma_f32_16x16x32_bf16 v[100:103], v[148:151], v[196:199], v[100:103]
	v_mfma_f32_16x16x32_bf16 v[96:99], v[156:159], v[196:199], v[96:99]
	v_mfma_f32_16x16x32_bf16 v[84:87], v[148:151], v[204:207], v[84:87]
	v_mfma_f32_16x16x32_bf16 v[80:83], v[156:159], v[204:207], v[80:83]
	s_setprio 0
	s_barrier
	s_add_i32 s55, s55, s67
	v_lshl_add_u64 v[208:209], s[10:11], 0, v[176:177]
	s_mov_b32 m0, s55
	ds_read_b128 v[160:163], v237 offset:16384
	ds_read_b128 v[164:167], v237 offset:17408
	ds_read_b128 v[168:171], v237 offset:18432
	ds_read_b128 v[172:175], v237 offset:19456
	ds_read_b128 v[192:195], v237 offset:20480
	ds_read_b128 v[196:199], v237 offset:21504
	ds_read_b128 v[200:203], v237 offset:22528
	ds_read_b128 v[204:207], v237 offset:23552
	global_load_lds_dwordx4 v[208:209], off
	s_add_i32 m0, s55, 0x2000
	s_add_u32 s60, s10, 0x40000
	v_lshl_add_u64 v[210:211], s[10:11], 0, v[182:183]
	s_addc_u32 s61, s11, 0
	s_add_i32 s55, s70, s67
	global_load_lds_dwordx4 v[210:211], off
	v_lshl_add_u64 v[212:213], s[60:61], 0, v[176:177]
	s_mov_b32 m0, s55
	v_lshl_add_u64 v[214:215], s[12:13], 0, v[184:185]
	global_load_lds_dwordx4 v[212:213], off
	v_lshl_add_u64 v[212:213], s[60:61], 0, v[182:183]
	s_add_i32 m0, s55, 0x2000
	s_nop 0
	global_load_lds_dwordx4 v[212:213], off
	v_lshl_add_u64 v[212:213], s[12:13], 0, v[186:187]
	s_mov_b32 m0, s65
	s_nop 0
	global_load_lds_dwordx4 v[212:213], off
	s_mov_b32 m0, s36
	s_nop 0
	global_load_lds_dwordx4 v[214:215], off
	s_waitcnt vmcnt(8)
	s_waitcnt lgkmcnt(0)
	s_barrier
; #define PG8_STAGE(bufoff, gbase, voff) do { _Pragma("unroll") for (int _i = 0; _i < 2; ++_i) \
;         __builtin_amdgcn_global_load_lds((const unsigned*)((const char*)(gbase) + (voff)[_i]), (PG8_LAS unsigned*)(lds + (bufoff) + ldsw + _i * 8192), 16, 0, 0); } while (0)
; #define PG8_LDA(dst, b, h) do { _Pragma("unroll") for (int m = 0; m < 4; ++m) _Pragma("unroll") for (int k = 0; k < 2; ++k) dst[m][k] = *(const PG8_LAS bf16x8*)(lds + PG8_SA(b, h) + aoff + m * 2048 + k * 1024); } while (0)
; #define PG8_LDB(dst, b, h) do { _Pragma("unroll") for (int n = 0; n < 2; ++n) _Pragma("unroll") for (int k = 0; k < 2; ++k) dst[n][k] = *(const PG8_LAS bf16x8*)(lds + PG8_SB(b, h) + boff + n * 2048 + k * 1024); } while (0)
; #define PG8_MMA(ai, bj, At, Bt) do { __builtin_amdgcn_s_setprio(1); _Pragma("unroll") for (int m = 0; m < 4; ++m) _Pragma("unroll") for (int n = 0; n < 2; ++n) _Pragma("unroll") for (int k = 0; k < 2; ++k) \
;         acc[ai][bj][m][n] = __builtin_amdgcn_mfma_f32_16x16x32_bf16(Bt[n][k], At[m][k], acc[ai][bj][m][n], 0, 0, 0); __builtin_amdgcn_s_setprio(0); } while (0)
; #define PG8_WAIT_V(n) asm volatile("s_waitcnt vmcnt(" #n ")" ::: "memory")
; #define PG8_WAIT_L(n) asm volatile("s_waitcnt lgkmcnt(" #n ")" ::: "memory")
; #define PG8_BAR __builtin_amdgcn_s_barrier()
; #define PG8_SCHED __builtin_amdgcn_sched_barrier(0)
; template <class Epi, class Sched, bool ALIGN_EPI = false, bool SP2 = false>
; __device__ __forceinline__ void gemm_phase(PG8_LAS unsigned char* lds, const Gemm g, const Sched& S, const Epi& E) {
;     ...
;             PG8_WAIT_V(8); PG8_WAIT_L(0); PG8_BAR; PG8_MMA(1, 0, At, B0); PG8_MMA(1, 1, At, B1); PG8_BAR; PG8_SCHED;
;             PG8_LDB(B0, 1, 0); PG8_LDB(B1, 1, 1); PG8_SCHED; PG8_LDA(At, 1, 0); PG8_STAGE(PG8_SA(0, 1), a2 + hstep, voffA);
;             PG8_WAIT_V(8); PG8_WAIT_L(0); PG8_BAR; PG8_MMA(0, 0, At, B0); PG8_MMA(0, 1, At, B1); PG8_BAR; PG8_SCHED;
	s_setprio 1
	s_waitcnt lgkmcnt(0)
	v_mfma_f32_16x16x32_bf16 v[76:79], v[48:51], v[160:163], v[76:79]
	v_mfma_f32_16x16x32_bf16 v[72:75], v[64:67], v[160:163], v[72:75]
	v_mfma_f32_16x16x32_bf16 v[44:47], v[48:51], v[168:171], v[44:47]
	v_mfma_f32_16x16x32_bf16 v[40:43], v[64:67], v[168:171], v[40:43]
	v_mfma_f32_16x16x32_bf16 v[28:31], v[48:51], v[192:195], v[28:31]
	v_mfma_f32_16x16x32_bf16 v[24:27], v[64:67], v[192:195], v[24:27]
	v_mfma_f32_16x16x32_bf16 v[12:15], v[48:51], v[200:203], v[12:15]
	v_mfma_f32_16x16x32_bf16 v[8:11], v[64:67], v[200:203], v[8:11]
	v_mfma_f32_16x16x32_bf16 v[76:79], v[56:59], v[164:167], v[76:79]
	v_mfma_f32_16x16x32_bf16 v[72:75], v[68:71], v[164:167], v[72:75]
	v_mfma_f32_16x16x32_bf16 v[44:47], v[56:59], v[172:175], v[44:47]
	v_mfma_f32_16x16x32_bf16 v[40:43], v[68:71], v[172:175], v[40:43]
	v_mfma_f32_16x16x32_bf16 v[28:31], v[56:59], v[196:199], v[28:31]
	v_mfma_f32_16x16x32_bf16 v[24:27], v[68:71], v[196:199], v[24:27]
	v_mfma_f32_16x16x32_bf16 v[12:15], v[56:59], v[204:207], v[12:15]
	v_mfma_f32_16x16x32_bf16 v[8:11], v[68:71], v[204:207], v[8:11]
	s_setprio 0
	s_setprio 1
	v_mfma_f32_16x16x32_bf16 v[52:55], v[152:155], v[160:163], v[52:55]
	v_mfma_f32_16x16x32_bf16 v[36:39], v[144:147], v[168:171], v[36:39]
	v_mfma_f32_16x16x32_bf16 v[32:35], v[152:155], v[168:171], v[32:35]
	v_mfma_f32_16x16x32_bf16 v[20:23], v[144:147], v[192:195], v[20:23]
	v_mfma_f32_16x16x32_bf16 v[16:19], v[152:155], v[192:195], v[16:19]
	v_mfma_f32_16x16x32_bf16 v[4:7], v[144:147], v[200:203], v[4:7]
	v_mfma_f32_16x16x32_bf16 v[0:3], v[152:155], v[200:203], v[0:3]
	v_mfma_f32_16x16x32_bf16 v[48:51], v[144:147], v[160:163], v[60:63]
	v_mfma_f32_16x16x32_bf16 v[52:55], v[156:159], v[164:167], v[52:55]
	v_mfma_f32_16x16x32_bf16 v[36:39], v[148:151], v[172:175], v[36:39]
	v_mfma_f32_16x16x32_bf16 v[32:35], v[156:159], v[172:175], v[32:35]
	v_mfma_f32_16x16x32_bf16 v[20:23], v[148:151], v[196:199], v[20:23]
	v_mfma_f32_16x16x32_bf16 v[16:19], v[156:159], v[196:199], v[16:19]
	v_mfma_f32_16x16x32_bf16 v[4:7], v[148:151], v[204:207], v[4:7]
	v_mfma_f32_16x16x32_bf16 v[0:3], v[156:159], v[204:207], v[0:3]
	v_mfma_f32_16x16x32_bf16 v[48:51], v[148:151], v[164:167], v[48:51]
	s_setprio 0
	s_barrier
	s_add_i32 s55, 0, 0x18000
	s_add_i32 s60, 0, 0x1c000
	v_add_u32_e32 v68, s55, v235
	v_add_u32_e32 v156, s60, v235
	ds_read_b128 v[56:59], v68
	ds_read_b128 v[60:63], v68 offset:1024
	ds_read_b128 v[64:67], v68 offset:2048
	ds_read_b128 v[68:71], v68 offset:3072
	ds_read_b128 v[144:147], v156
	ds_read_b128 v[148:151], v156 offset:1024
	ds_read_b128 v[152:155], v156 offset:2048
	ds_read_b128 v[156:159], v156 offset:3072
	s_add_u32 s12, s12, 0x40000
	s_addc_u32 s13, s13, 0
	s_mov_b32 m0, s37
	v_lshl_add_u64 v[216:217], s[12:13], 0, v[186:187]
	ds_read_b128 v[160:163], v237 offset:32768
	ds_read_b128 v[164:167], v237 offset:33792
	ds_read_b128 v[168:171], v237 offset:34816
	ds_read_b128 v[172:175], v237 offset:35840
	ds_read_b128 v[192:195], v237 offset:36864
	ds_read_b128 v[196:199], v237 offset:37888
	ds_read_b128 v[200:203], v237 offset:38912
	ds_read_b128 v[204:207], v237 offset:39936
	global_load_lds_dwordx4 v[216:217], off
	v_lshl_add_u64 v[216:217], s[12:13], 0, v[184:185]
	s_mov_b32 m0, s71
	s_nop 0
	global_load_lds_dwordx4 v[216:217], off
	s_waitcnt vmcnt(8)
	s_waitcnt lgkmcnt(0)
	s_barrier
	s_setprio 1
	s_waitcnt lgkmcnt(0)
	v_mfma_f32_16x16x32_bf16 v[140:143], v[56:59], v[160:163], v[140:143]
	v_mfma_f32_16x16x32_bf16 v[136:139], v[64:67], v[160:163], v[136:139]
	v_mfma_f32_16x16x32_bf16 v[124:127], v[56:59], v[168:171], v[124:127]
	v_mfma_f32_16x16x32_bf16 v[120:123], v[64:67], v[168:171], v[120:123]
	v_mfma_f32_16x16x32_bf16 v[108:111], v[56:59], v[192:195], v[108:111]
	v_mfma_f32_16x16x32_bf16 v[104:107], v[64:67], v[192:195], v[104:107]
	v_mfma_f32_16x16x32_bf16 v[92:95], v[56:59], v[200:203], v[92:95]
	v_mfma_f32_16x16x32_bf16 v[88:91], v[64:67], v[200:203], v[88:91]
	v_mfma_f32_16x16x32_bf16 v[140:143], v[60:63], v[164:167], v[140:143]
	v_mfma_f32_16x16x32_bf16 v[136:139], v[68:71], v[164:167], v[136:139]
	v_mfma_f32_16x16x32_bf16 v[124:127], v[60:63], v[172:175], v[124:127]
	v_mfma_f32_16x16x32_bf16 v[120:123], v[68:71], v[172:175], v[120:123]
	v_mfma_f32_16x16x32_bf16 v[108:111], v[60:63], v[196:199], v[108:111]
	v_mfma_f32_16x16x32_bf16 v[104:107], v[68:71], v[196:199], v[104:107]
	v_mfma_f32_16x16x32_bf16 v[92:95], v[60:63], v[204:207], v[92:95]
	v_mfma_f32_16x16x32_bf16 v[88:91], v[68:71], v[204:207], v[88:91]
	s_setprio 0
	s_setprio 1
	v_mfma_f32_16x16x32_bf16 v[132:135], v[144:147], v[160:163], v[132:135]
	v_mfma_f32_16x16x32_bf16 v[128:131], v[152:155], v[160:163], v[128:131]
	v_mfma_f32_16x16x32_bf16 v[116:119], v[144:147], v[168:171], v[116:119]
	v_mfma_f32_16x16x32_bf16 v[112:115], v[152:155], v[168:171], v[112:115]
	v_mfma_f32_16x16x32_bf16 v[100:103], v[144:147], v[192:195], v[100:103]
	v_mfma_f32_16x16x32_bf16 v[96:99], v[152:155], v[192:195], v[96:99]
	v_mfma_f32_16x16x32_bf16 v[84:87], v[144:147], v[200:203], v[84:87]
	v_mfma_f32_16x16x32_bf16 v[80:83], v[152:155], v[200:203], v[80:83]
	v_mfma_f32_16x16x32_bf16 v[132:135], v[148:151], v[164:167], v[132:135]
	v_mfma_f32_16x16x32_bf16 v[128:131], v[156:159], v[164:167], v[128:131]
	v_mfma_f32_16x16x32_bf16 v[116:119], v[148:151], v[172:175], v[116:119]
	v_mfma_f32_16x16x32_bf16 v[112:115], v[156:159], v[172:175], v[112:115]
	v_mfma_f32_16x16x32_bf16 v[100:103], v[148:151], v[196:199], v[100:103]
	v_mfma_f32_16x16x32_bf16 v[96:99], v[156:159], v[196:199], v[96:99]
	v_mfma_f32_16x16x32_bf16 v[84:87], v[148:151], v[204:207], v[84:87]
	v_mfma_f32_16x16x32_bf16 v[80:83], v[156:159], v[204:207], v[80:83]
	s_setprio 0
	s_barrier
; #define PG8_STAGE(bufoff, gbase, voff) do { _Pragma("unroll") for (int _i = 0; _i < 2; ++_i) \
;         __builtin_amdgcn_global_load_lds((const unsigned*)((const char*)(gbase) + (voff)[_i]), (PG8_LAS unsigned*)(lds + (bufoff) + ldsw + _i * 8192), 16, 0, 0); } while (0)
; #define PG8_LDA(dst, b, h) do { _Pragma("unroll") for (int m = 0; m < 4; ++m) _Pragma("unroll") for (int k = 0; k < 2; ++k) dst[m][k] = *(const PG8_LAS bf16x8*)(lds + PG8_SA(b, h) + aoff + m * 2048 + k * 1024); } while (0)
; #define PG8_MMA(ai, bj, At, Bt) do { __builtin_amdgcn_s_setprio(1); _Pragma("unroll") for (int m = 0; m < 4; ++m) _Pragma("unroll") for (int n = 0; n < 2; ++n) _Pragma("unroll") for (int k = 0; k < 2; ++k) \
;         acc[ai][bj][m][n] = __builtin_amdgcn_mfma_f32_16x16x32_bf16(Bt[n][k], At[m][k], acc[ai][bj][m][n], 0, 0, 0); __builtin_amdgcn_s_setprio(0); } while (0)
; #define PG8_WAIT_V(n) asm volatile("s_waitcnt vmcnt(" #n ")" ::: "memory")
; #define PG8_WAIT_L(n) asm volatile("s_waitcnt lgkmcnt(" #n ")" ::: "memory")
; #define PG8_BAR __builtin_amdgcn_s_barrier()
; #define PG8_SCHED __builtin_amdgcn_sched_barrier(0)
; template <class Epi, class Sched, bool ALIGN_EPI = false, bool SP2 = false>
; __device__ __forceinline__ void gemm_phase(PG8_LAS unsigned char* lds, const Gemm g, const Sched& S, const Epi& E) {
;     ...
;         for (int t = 0; t < nt; t += 2) {
;     ...
;             PG8_LDA(At, 1, 1); PG8_STAGE(PG8_SB(1, 0), b3, voffB); PG8_STAGE(PG8_SB(1, 1), b3 + hstep, voffB); PG8_STAGE(PG8_SA(1, 0), a3, voffA);
;             PG8_WAIT_V(8); PG8_WAIT_L(0); PG8_BAR; PG8_MMA(1, 0, At, B0); PG8_MMA(1, 1, At, B1); PG8_BAR; PG8_SCHED;
	s_add_i32 s12, s55, s67
	v_lshl_add_u64 v[208:209], v[208:209], 0, s[88:89]
	s_mov_b32 m0, s12
	ds_read_b128 v[160:163], v237 offset:49152
	ds_read_b128 v[164:167], v237 offset:50176
	ds_read_b128 v[168:171], v237 offset:51200
	ds_read_b128 v[172:175], v237 offset:52224
	ds_read_b128 v[192:195], v237 offset:53248
	ds_read_b128 v[196:199], v237 offset:54272
	ds_read_b128 v[200:203], v237 offset:55296
	ds_read_b128 v[204:207], v237 offset:56320
	global_load_lds_dwordx4 v[208:209], off
	s_add_i32 m0, s12, 0x2000
	s_add_u32 s10, s10, 0x40080
	v_lshl_add_u64 v[208:209], v[210:211], 0, s[88:89]
	s_addc_u32 s11, s11, 0
	s_add_i32 s12, s60, s67
	global_load_lds_dwordx4 v[208:209], off
	v_lshl_add_u64 v[208:209], s[10:11], 0, v[176:177]
	s_mov_b32 m0, s12
	s_nop 0
	global_load_lds_dwordx4 v[208:209], off
	v_lshl_add_u64 v[208:209], s[10:11], 0, v[182:183]
	s_add_i32 m0, s12, 0x2000
	s_nop 0
	global_load_lds_dwordx4 v[208:209], off
	v_lshl_add_u64 v[208:209], v[212:213], 0, s[88:89]
	s_mov_b32 m0, s95
	s_nop 0
	global_load_lds_dwordx4 v[208:209], off
	v_lshl_add_u64 v[208:209], v[214:215], 0, s[88:89]
	s_mov_b32 m0, s54
	s_nop 0
	global_load_lds_dwordx4 v[208:209], off
	s_waitcnt vmcnt(8)
	s_waitcnt lgkmcnt(0)
	s_barrier
	s_setprio 1
	s_waitcnt lgkmcnt(0)
	v_mfma_f32_16x16x32_bf16 v[76:79], v[56:59], v[160:163], v[76:79]
	v_mfma_f32_16x16x32_bf16 v[72:75], v[64:67], v[160:163], v[72:75]
	v_mfma_f32_16x16x32_bf16 v[44:47], v[56:59], v[168:171], v[44:47]
	v_mfma_f32_16x16x32_bf16 v[40:43], v[64:67], v[168:171], v[40:43]
	v_mfma_f32_16x16x32_bf16 v[28:31], v[56:59], v[192:195], v[28:31]
	v_mfma_f32_16x16x32_bf16 v[24:27], v[64:67], v[192:195], v[24:27]
	v_mfma_f32_16x16x32_bf16 v[12:15], v[56:59], v[200:203], v[12:15]
	v_mfma_f32_16x16x32_bf16 v[8:11], v[64:67], v[200:203], v[8:11]
	v_mfma_f32_16x16x32_bf16 v[76:79], v[60:63], v[164:167], v[76:79]
	v_mfma_f32_16x16x32_bf16 v[72:75], v[68:71], v[164:167], v[72:75]
	v_mfma_f32_16x16x32_bf16 v[44:47], v[60:63], v[172:175], v[44:47]
	v_mfma_f32_16x16x32_bf16 v[40:43], v[68:71], v[172:175], v[40:43]
	v_mfma_f32_16x16x32_bf16 v[28:31], v[60:63], v[196:199], v[28:31]
	v_mfma_f32_16x16x32_bf16 v[24:27], v[68:71], v[196:199], v[24:27]
	v_mfma_f32_16x16x32_bf16 v[12:15], v[60:63], v[204:207], v[12:15]
	v_mfma_f32_16x16x32_bf16 v[8:11], v[68:71], v[204:207], v[8:11]
	s_setprio 0
	s_setprio 1
	v_mfma_f32_16x16x32_bf16 v[48:51], v[144:147], v[160:163], v[48:51]
	v_mfma_f32_16x16x32_bf16 v[60:63], v[148:151], v[164:167], v[48:51]
	v_mfma_f32_16x16x32_bf16 v[48:51], v[152:155], v[160:163], v[52:55]
	v_mfma_f32_16x16x32_bf16 v[36:39], v[144:147], v[168:171], v[36:39]
	v_mfma_f32_16x16x32_bf16 v[32:35], v[152:155], v[168:171], v[32:35]
	v_mfma_f32_16x16x32_bf16 v[20:23], v[144:147], v[192:195], v[20:23]
	v_mfma_f32_16x16x32_bf16 v[16:19], v[152:155], v[192:195], v[16:19]
	v_mfma_f32_16x16x32_bf16 v[4:7], v[144:147], v[200:203], v[4:7]
	v_mfma_f32_16x16x32_bf16 v[0:3], v[152:155], v[200:203], v[0:3]
	v_mfma_f32_16x16x32_bf16 v[52:55], v[156:159], v[164:167], v[48:51]
	v_mfma_f32_16x16x32_bf16 v[36:39], v[148:151], v[172:175], v[36:39]
	v_mfma_f32_16x16x32_bf16 v[32:35], v[156:159], v[172:175], v[32:35]
	v_mfma_f32_16x16x32_bf16 v[20:23], v[148:151], v[196:199], v[20:23]
	v_mfma_f32_16x16x32_bf16 v[16:19], v[156:159], v[196:199], v[16:19]
	v_mfma_f32_16x16x32_bf16 v[4:7], v[148:151], v[204:207], v[4:7]
	v_mfma_f32_16x16x32_bf16 v[0:3], v[156:159], v[204:207], v[0:3]
	s_add_i32 s69, s69, 2
	s_add_u32 s59, s59, 0x100
	s_addc_u32 s68, s68, 0
	s_add_u32 s8, s8, 0x100
	s_addc_u32 s9, s9, 0
	s_cmp_gt_u32 s69, 13
	s_setprio 0
	s_barrier
	s_cbranch_scc0 .LBB0_910
	s_and_b64 vcc, exec, s[34:35]
	s_cbranch_vccz .LBB0_913
	s_barrier

; #define PG8_STAGE(bufoff, gbase, voff) do { _Pragma("unroll") for (int _i = 0; _i < 2; ++_i) \
;         __builtin_amdgcn_global_load_lds((const unsigned*)((const char*)(gbase) + (voff)[_i]), (PG8_LAS unsigned*)(lds + (bufoff) + ldsw + _i * 8192), 16, 0, 0); } while (0)
; #define PG8_LDA(dst, b, h) do { _Pragma("unroll") for (int m = 0; m < 4; ++m) _Pragma("unroll") for (int k = 0; k < 2; ++k) dst[m][k] = *(const PG8_LAS bf16x8*)(lds + PG8_SA(b, h) + aoff + m * 2048 + k * 1024); } while (0)
; #define PG8_LDB(dst, b, h) do { _Pragma("unroll") for (int n = 0; n < 2; ++n) _Pragma("unroll") for (int k = 0; k < 2; ++k) dst[n][k] = *(const PG8_LAS bf16x8*)(lds + PG8_SB(b, h) + boff + n * 2048 + k * 1024); } while (0)
; #define PG8_MMA(ai, bj, At, Bt) do { __builtin_amdgcn_s_setprio(1); _Pragma("unroll") for (int m = 0; m < 4; ++m) _Pragma("unroll") for (int n = 0; n < 2; ++n) _Pragma("unroll") for (int k = 0; k < 2; ++k) \
;         acc[ai][bj][m][n] = __builtin_amdgcn_mfma_f32_16x16x32_bf16(Bt[n][k], At[m][k], acc[ai][bj][m][n], 0, 0, 0); __builtin_amdgcn_s_setprio(0); } while (0)
; #define PG8_WAIT_V(n) asm volatile("s_waitcnt vmcnt(" #n ")" ::: "memory")
; #define PG8_WAIT_L(n) asm volatile("s_waitcnt lgkmcnt(" #n ")" ::: "memory")
; #define PG8_BAR __builtin_amdgcn_s_barrier()
; #define PG8_SCHED __builtin_amdgcn_sched_barrier(0)
; template <class Epi, class Sched, bool ALIGN_EPI = false, bool SP2 = false>
; __device__ __forceinline__ void gemm_phase(PG8_LAS unsigned char* lds, const Gemm g, const Sched& S, const Epi& E) {
;     ...
;             const bool last = (t == nt - 2);
;             const char* a1 = cA + (size_t)(t + 1) * kstep;
;             const char* a2 = last ? nA : cA + (size_t)(t + 2) * kstep; const char* b2 = last ? nB : cB + (size_t)(t + 2) * kstep;
;             const char* a3 = a2 + kstep; const char* b3 = b2 + kstep;
;             if (last && has_next) S.a_ready(nxt);
;             if constexpr (SP2) {
;             PG8_LDB(B0, 0, 0); PG8_LDB(B1, 0, 1); PG8_SCHED; PG8_LDA(At, 0, 0); PG8_STAGE(PG8_SA(1, 1), a1 + hstep, voffA);
;             PG8_WAIT_V(8); PG8_WAIT_L(0); PG8_BAR; PG8_MMA(0, 0, At, B0); PG8_MMA(0, 1, At, B1); PG8_BAR; PG8_SCHED;
;             PG8_LDA(At, 0, 1); PG8_STAGE(PG8_SB(0, 0), b2, voffB); PG8_STAGE(PG8_SB(0, 1), b2 + hstep, voffB); PG8_STAGE(PG8_SA(0, 0), a2, voffA);
.LBB0_1089:
	s_add_u32 s30, s28, 0xfffc0080
	s_addc_u32 s31, s29, -1
	s_add_i32 s55, 0, 0x10000
	s_cmp_eq_u32 s62, 12
	s_cselect_b32 s35, s1, s31
	s_cselect_b32 s34, s21, s30
	s_cselect_b32 s31, s19, s59
	s_cselect_b32 s30, s27, s58
	s_add_i32 s63, 0, 0x14000
	v_add_u32_e32 v156, s55, v153
	v_add_u32_e32 v172, s63, v153
	ds_read_b128 v[80:83], v156
	ds_read_b128 v[84:87], v156 offset:1024
	ds_read_b128 v[148:151], v156 offset:2048
	ds_read_b128 v[156:159], v156 offset:3072
	ds_read_b128 v[160:163], v172
	ds_read_b128 v[164:167], v172 offset:1024
	ds_read_b128 v[168:171], v172 offset:2048
	ds_read_b128 v[172:175], v172 offset:3072
	v_lshl_add_u64 v[214:215], s[28:29], 0, v[146:147]
	s_add_i32 m0, s49, 0xc000
	ds_read_b128 v[182:185], v155
	ds_read_b128 v[186:189], v155 offset:1024
	ds_read_b128 v[190:193], v155 offset:2048
	ds_read_b128 v[194:197], v155 offset:3072
	ds_read_b128 v[198:201], v155 offset:4096
	ds_read_b128 v[202:205], v155 offset:5120
	ds_read_b128 v[206:209], v155 offset:6144
	ds_read_b128 v[210:213], v155 offset:7168
	global_load_lds_dwordx4 v[214:215], off
	v_lshl_add_u64 v[214:215], s[28:29], 0, v[144:145]
	s_add_i32 m0, s49, 0xe000
	s_nop 0
	global_load_lds_dwordx4 v[214:215], off
	s_waitcnt vmcnt(8)
	s_waitcnt lgkmcnt(0)
	s_barrier
	s_setprio 1
	s_waitcnt lgkmcnt(0)
	v_mfma_f32_16x16x32_bf16 v[128:131], v[80:83], v[182:185], v[128:131]
	v_mfma_f32_16x16x32_bf16 v[124:127], v[148:151], v[182:185], v[124:127]
	v_mfma_f32_16x16x32_bf16 v[112:115], v[80:83], v[190:193], v[112:115]
	v_mfma_f32_16x16x32_bf16 v[104:107], v[148:151], v[190:193], v[104:107]
	v_mfma_f32_16x16x32_bf16 v[96:99], v[80:83], v[198:201], v[96:99]
	v_mfma_f32_16x16x32_bf16 v[88:91], v[148:151], v[198:201], v[88:91]
	v_mfma_f32_16x16x32_bf16 v[72:75], v[80:83], v[206:209], v[72:75]
	v_mfma_f32_16x16x32_bf16 v[64:67], v[148:151], v[206:209], v[64:67]
	v_mfma_f32_16x16x32_bf16 v[128:131], v[84:87], v[186:189], v[128:131]
	v_mfma_f32_16x16x32_bf16 v[124:127], v[156:159], v[186:189], v[124:127]
	v_mfma_f32_16x16x32_bf16 v[112:115], v[84:87], v[194:197], v[112:115]
	v_mfma_f32_16x16x32_bf16 v[104:107], v[156:159], v[194:197], v[104:107]
	v_mfma_f32_16x16x32_bf16 v[96:99], v[84:87], v[202:205], v[96:99]
	v_mfma_f32_16x16x32_bf16 v[88:91], v[156:159], v[202:205], v[88:91]
	v_mfma_f32_16x16x32_bf16 v[72:75], v[84:87], v[210:213], v[72:75]
	v_mfma_f32_16x16x32_bf16 v[64:67], v[156:159], v[210:213], v[64:67]
	s_setprio 0
	s_setprio 1
	v_mfma_f32_16x16x32_bf16 v[132:135], v[160:163], v[182:185], v[132:135]
	v_mfma_f32_16x16x32_bf16 v[120:123], v[168:171], v[182:185], v[120:123]
	v_mfma_f32_16x16x32_bf16 v[116:119], v[160:163], v[190:193], v[116:119]
	v_mfma_f32_16x16x32_bf16 v[108:111], v[168:171], v[190:193], v[108:111]
	v_mfma_f32_16x16x32_bf16 v[100:103], v[160:163], v[198:201], v[100:103]
	v_mfma_f32_16x16x32_bf16 v[92:95], v[168:171], v[198:201], v[92:95]
	v_mfma_f32_16x16x32_bf16 v[76:79], v[160:163], v[206:209], v[76:79]
	v_mfma_f32_16x16x32_bf16 v[68:71], v[168:171], v[206:209], v[68:71]
	v_mfma_f32_16x16x32_bf16 v[132:135], v[164:167], v[186:189], v[132:135]
	v_mfma_f32_16x16x32_bf16 v[120:123], v[172:175], v[186:189], v[120:123]
	v_mfma_f32_16x16x32_bf16 v[116:119], v[164:167], v[194:197], v[116:119]
	v_mfma_f32_16x16x32_bf16 v[108:111], v[172:175], v[194:197], v[108:111]
	v_mfma_f32_16x16x32_bf16 v[100:103], v[164:167], v[202:205], v[100:103]
	v_mfma_f32_16x16x32_bf16 v[92:95], v[172:175], v[202:205], v[92:95]
	v_mfma_f32_16x16x32_bf16 v[76:79], v[164:167], v[210:213], v[76:79]
	v_mfma_f32_16x16x32_bf16 v[68:71], v[172:175], v[210:213], v[68:71]
	s_setprio 0
	s_barrier
	s_add_i32 s55, s55, s45
	v_lshl_add_u64 v[214:215], s[30:31], 0, v[138:139]
	s_mov_b32 m0, s55
	ds_read_b128 v[182:185], v155 offset:16384
	ds_read_b128 v[186:189], v155 offset:17408
	ds_read_b128 v[190:193], v155 offset:18432
	ds_read_b128 v[194:197], v155 offset:19456
	ds_read_b128 v[198:201], v155 offset:20480
	ds_read_b128 v[202:205], v155 offset:21504
	ds_read_b128 v[206:209], v155 offset:22528
	ds_read_b128 v[210:213], v155 offset:23552
	global_load_lds_dwordx4 v[214:215], off
	s_add_i32 m0, s55, 0x2000
	s_add_u32 s60, s30, 0x40000
	v_lshl_add_u64 v[216:217], s[30:31], 0, v[142:143]
	s_addc_u32 s61, s31, 0
	s_add_i32 s55, s63, s45
	global_load_lds_dwordx4 v[216:217], off
	v_lshl_add_u64 v[218:219], s[60:61], 0, v[138:139]
	s_mov_b32 m0, s55
	v_lshl_add_u64 v[220:221], s[34:35], 0, v[140:141]
	global_load_lds_dwordx4 v[218:219], off
	v_lshl_add_u64 v[218:219], s[60:61], 0, v[142:143]
	s_add_i32 m0, s55, 0x2000
	s_nop 0
	global_load_lds_dwordx4 v[218:219], off
	v_lshl_add_u64 v[218:219], s[34:35], 0, v[136:137]
	s_mov_b32 m0, s49
	s_nop 0
	global_load_lds_dwordx4 v[218:219], off
	s_mov_b32 m0, s51
	s_nop 0
	global_load_lds_dwordx4 v[220:221], off
	s_waitcnt vmcnt(8)
	s_waitcnt lgkmcnt(0)
	s_barrier
; #define PG8_STAGE(bufoff, gbase, voff) do { _Pragma("unroll") for (int _i = 0; _i < 2; ++_i) \
;         __builtin_amdgcn_global_load_lds((const unsigned*)((const char*)(gbase) + (voff)[_i]), (PG8_LAS unsigned*)(lds + (bufoff) + ldsw + _i * 8192), 16, 0, 0); } while (0)
; #define PG8_LDA(dst, b, h) do { _Pragma("unroll") for (int m = 0; m < 4; ++m) _Pragma("unroll") for (int k = 0; k < 2; ++k) dst[m][k] = *(const PG8_LAS bf16x8*)(lds + PG8_SA(b, h) + aoff + m * 2048 + k * 1024); } while (0)
; #define PG8_LDB(dst, b, h) do { _Pragma("unroll") for (int n = 0; n < 2; ++n) _Pragma("unroll") for (int k = 0; k < 2; ++k) dst[n][k] = *(const PG8_LAS bf16x8*)(lds + PG8_SB(b, h) + boff + n * 2048 + k * 1024); } while (0)
; #define PG8_MMA(ai, bj, At, Bt) do { __builtin_amdgcn_s_setprio(1); _Pragma("unroll") for (int m = 0; m < 4; ++m) _Pragma("unroll") for (int n = 0; n < 2; ++n) _Pragma("unroll") for (int k = 0; k < 2; ++k) \
;         acc[ai][bj][m][n] = __builtin_amdgcn_mfma_f32_16x16x32_bf16(Bt[n][k], At[m][k], acc[ai][bj][m][n], 0, 0, 0); __builtin_amdgcn_s_setprio(0); } while (0)
; #define PG8_WAIT_V(n) asm volatile("s_waitcnt vmcnt(" #n ")" ::: "memory")
; #define PG8_WAIT_L(n) asm volatile("s_waitcnt lgkmcnt(" #n ")" ::: "memory")
; #define PG8_BAR __builtin_amdgcn_s_barrier()
; #define PG8_SCHED __builtin_amdgcn_sched_barrier(0)
; template <class Epi, class Sched, bool ALIGN_EPI = false, bool SP2 = false>
; __device__ __forceinline__ void gemm_phase(PG8_LAS unsigned char* lds, const Gemm g, const Sched& S, const Epi& E) {
;     ...
;             PG8_WAIT_V(8); PG8_WAIT_L(0); PG8_BAR; PG8_MMA(1, 0, At, B0); PG8_MMA(1, 1, At, B1); PG8_BAR; PG8_SCHED;
;             PG8_LDB(B0, 1, 0); PG8_LDB(B1, 1, 1); PG8_SCHED; PG8_LDA(At, 1, 0); PG8_STAGE(PG8_SA(0, 1), a2 + hstep, voffA);
;             PG8_WAIT_V(8); PG8_WAIT_L(0); PG8_BAR; PG8_MMA(0, 0, At, B0); PG8_MMA(0, 1, At, B1); PG8_BAR; PG8_SCHED;
	s_setprio 1
	s_waitcnt lgkmcnt(0)
	v_mfma_f32_16x16x32_bf16 v[56:59], v[80:83], v[182:185], v[56:59]
	v_mfma_f32_16x16x32_bf16 v[48:51], v[148:151], v[182:185], v[48:51]
	v_mfma_f32_16x16x32_bf16 v[40:43], v[80:83], v[190:193], v[40:43]
	v_mfma_f32_16x16x32_bf16 v[32:35], v[148:151], v[190:193], v[32:35]
	v_mfma_f32_16x16x32_bf16 v[24:27], v[80:83], v[198:201], v[24:27]
	v_mfma_f32_16x16x32_bf16 v[16:19], v[148:151], v[198:201], v[16:19]
	v_mfma_f32_16x16x32_bf16 v[8:11], v[80:83], v[206:209], v[8:11]
	v_mfma_f32_16x16x32_bf16 v[0:3], v[148:151], v[206:209], v[0:3]
	v_mfma_f32_16x16x32_bf16 v[56:59], v[84:87], v[186:189], v[56:59]
	v_mfma_f32_16x16x32_bf16 v[48:51], v[156:159], v[186:189], v[48:51]
	v_mfma_f32_16x16x32_bf16 v[40:43], v[84:87], v[194:197], v[40:43]
	v_mfma_f32_16x16x32_bf16 v[32:35], v[156:159], v[194:197], v[32:35]
	v_mfma_f32_16x16x32_bf16 v[24:27], v[84:87], v[202:205], v[24:27]
	v_mfma_f32_16x16x32_bf16 v[16:19], v[156:159], v[202:205], v[16:19]
	v_mfma_f32_16x16x32_bf16 v[8:11], v[84:87], v[210:213], v[8:11]
	v_mfma_f32_16x16x32_bf16 v[0:3], v[156:159], v[210:213], v[0:3]
	s_setprio 0
	s_setprio 1
	v_mfma_f32_16x16x32_bf16 v[60:63], v[160:163], v[182:185], v[60:63]
	v_mfma_f32_16x16x32_bf16 v[52:55], v[168:171], v[182:185], v[52:55]
	v_mfma_f32_16x16x32_bf16 v[44:47], v[160:163], v[190:193], v[44:47]
	v_mfma_f32_16x16x32_bf16 v[36:39], v[168:171], v[190:193], v[36:39]
	v_mfma_f32_16x16x32_bf16 v[28:31], v[160:163], v[198:201], v[28:31]
	v_mfma_f32_16x16x32_bf16 v[20:23], v[168:171], v[198:201], v[20:23]
	v_mfma_f32_16x16x32_bf16 v[12:15], v[160:163], v[206:209], v[12:15]
	v_mfma_f32_16x16x32_bf16 v[4:7], v[168:171], v[206:209], v[4:7]
	v_mfma_f32_16x16x32_bf16 v[60:63], v[164:167], v[186:189], v[60:63]
	v_mfma_f32_16x16x32_bf16 v[52:55], v[172:175], v[186:189], v[52:55]
	v_mfma_f32_16x16x32_bf16 v[44:47], v[164:167], v[194:197], v[44:47]
	v_mfma_f32_16x16x32_bf16 v[36:39], v[172:175], v[194:197], v[36:39]
	v_mfma_f32_16x16x32_bf16 v[28:31], v[164:167], v[202:205], v[28:31]
	v_mfma_f32_16x16x32_bf16 v[20:23], v[172:175], v[202:205], v[20:23]
	v_mfma_f32_16x16x32_bf16 v[12:15], v[164:167], v[210:213], v[12:15]
	v_mfma_f32_16x16x32_bf16 v[4:7], v[172:175], v[210:213], v[4:7]
	s_setprio 0
	s_barrier
	s_add_i32 s55, 0, 0x18000
	s_add_i32 s60, 0, 0x1c000
	v_add_u32_e32 v156, s55, v153
	v_add_u32_e32 v172, s60, v153
	ds_read_b128 v[80:83], v156
	ds_read_b128 v[84:87], v156 offset:1024
	ds_read_b128 v[148:151], v156 offset:2048
	ds_read_b128 v[156:159], v156 offset:3072
	ds_read_b128 v[160:163], v172
	ds_read_b128 v[164:167], v172 offset:1024
	ds_read_b128 v[168:171], v172 offset:2048
	ds_read_b128 v[172:175], v172 offset:3072
	s_add_u32 s34, s34, 0x40000
	s_addc_u32 s35, s35, 0
	s_mov_b32 m0, s52
	v_lshl_add_u64 v[234:235], s[34:35], 0, v[136:137]
	ds_read_b128 v[182:185], v155 offset:32768
	ds_read_b128 v[186:189], v155 offset:33792
	ds_read_b128 v[190:193], v155 offset:34816
	ds_read_b128 v[194:197], v155 offset:35840
	ds_read_b128 v[198:201], v155 offset:36864
	ds_read_b128 v[202:205], v155 offset:37888
	ds_read_b128 v[206:209], v155 offset:38912
	ds_read_b128 v[210:213], v155 offset:39936
	global_load_lds_dwordx4 v[234:235], off
	v_lshl_add_u64 v[234:235], s[34:35], 0, v[140:141]
	s_mov_b32 m0, s53
	s_nop 0
	global_load_lds_dwordx4 v[234:235], off
	s_waitcnt vmcnt(8)
	s_waitcnt lgkmcnt(0)
	s_barrier
	s_setprio 1
	s_waitcnt lgkmcnt(0)
	v_mfma_f32_16x16x32_bf16 v[128:131], v[80:83], v[182:185], v[128:131]
	v_mfma_f32_16x16x32_bf16 v[124:127], v[148:151], v[182:185], v[124:127]
	v_mfma_f32_16x16x32_bf16 v[112:115], v[80:83], v[190:193], v[112:115]
	v_mfma_f32_16x16x32_bf16 v[104:107], v[148:151], v[190:193], v[104:107]
	v_mfma_f32_16x16x32_bf16 v[96:99], v[80:83], v[198:201], v[96:99]
	v_mfma_f32_16x16x32_bf16 v[88:91], v[148:151], v[198:201], v[88:91]
	v_mfma_f32_16x16x32_bf16 v[72:75], v[80:83], v[206:209], v[72:75]
	v_mfma_f32_16x16x32_bf16 v[64:67], v[148:151], v[206:209], v[64:67]
	v_mfma_f32_16x16x32_bf16 v[128:131], v[84:87], v[186:189], v[128:131]
	v_mfma_f32_16x16x32_bf16 v[124:127], v[156:159], v[186:189], v[124:127]
	v_mfma_f32_16x16x32_bf16 v[112:115], v[84:87], v[194:197], v[112:115]
	v_mfma_f32_16x16x32_bf16 v[104:107], v[156:159], v[194:197], v[104:107]
	v_mfma_f32_16x16x32_bf16 v[96:99], v[84:87], v[202:205], v[96:99]
	v_mfma_f32_16x16x32_bf16 v[88:91], v[156:159], v[202:205], v[88:91]
	v_mfma_f32_16x16x32_bf16 v[72:75], v[84:87], v[210:213], v[72:75]
	v_mfma_f32_16x16x32_bf16 v[64:67], v[156:159], v[210:213], v[64:67]
	s_setprio 0
	s_setprio 1
	v_mfma_f32_16x16x32_bf16 v[132:135], v[160:163], v[182:185], v[132:135]
	v_mfma_f32_16x16x32_bf16 v[120:123], v[168:171], v[182:185], v[120:123]
	v_mfma_f32_16x16x32_bf16 v[116:119], v[160:163], v[190:193], v[116:119]
	v_mfma_f32_16x16x32_bf16 v[108:111], v[168:171], v[190:193], v[108:111]
	v_mfma_f32_16x16x32_bf16 v[100:103], v[160:163], v[198:201], v[100:103]
	v_mfma_f32_16x16x32_bf16 v[92:95], v[168:171], v[198:201], v[92:95]
	v_mfma_f32_16x16x32_bf16 v[76:79], v[160:163], v[206:209], v[76:79]
	v_mfma_f32_16x16x32_bf16 v[68:71], v[168:171], v[206:209], v[68:71]
	v_mfma_f32_16x16x32_bf16 v[132:135], v[164:167], v[186:189], v[132:135]
	v_mfma_f32_16x16x32_bf16 v[120:123], v[172:175], v[186:189], v[120:123]
	v_mfma_f32_16x16x32_bf16 v[116:119], v[164:167], v[194:197], v[116:119]
	v_mfma_f32_16x16x32_bf16 v[108:111], v[172:175], v[194:197], v[108:111]
	v_mfma_f32_16x16x32_bf16 v[100:103], v[164:167], v[202:205], v[100:103]
	v_mfma_f32_16x16x32_bf16 v[92:95], v[172:175], v[202:205], v[92:95]
	v_mfma_f32_16x16x32_bf16 v[76:79], v[164:167], v[210:213], v[76:79]
	v_mfma_f32_16x16x32_bf16 v[68:71], v[172:175], v[210:213], v[68:71]
	s_setprio 0
	s_barrier
; #define PG8_STAGE(bufoff, gbase, voff) do { _Pragma("unroll") for (int _i = 0; _i < 2; ++_i) \
;         __builtin_amdgcn_global_load_lds((const unsigned*)((const char*)(gbase) + (voff)[_i]), (PG8_LAS unsigned*)(lds + (bufoff) + ldsw + _i * 8192), 16, 0, 0); } while (0)
; #define PG8_LDA(dst, b, h) do { _Pragma("unroll") for (int m = 0; m < 4; ++m) _Pragma("unroll") for (int k = 0; k < 2; ++k) dst[m][k] = *(const PG8_LAS bf16x8*)(lds + PG8_SA(b, h) + aoff + m * 2048 + k * 1024); } while (0)
; #define PG8_MMA(ai, bj, At, Bt) do { __builtin_amdgcn_s_setprio(1); _Pragma("unroll") for (int m = 0; m < 4; ++m) _Pragma("unroll") for (int n = 0; n < 2; ++n) _Pragma("unroll") for (int k = 0; k < 2; ++k) \
;         acc[ai][bj][m][n] = __builtin_amdgcn_mfma_f32_16x16x32_bf16(Bt[n][k], At[m][k], acc[ai][bj][m][n], 0, 0, 0); __builtin_amdgcn_s_setprio(0); } while (0)
; #define PG8_WAIT_V(n) asm volatile("s_waitcnt vmcnt(" #n ")" ::: "memory")
; #define PG8_WAIT_L(n) asm volatile("s_waitcnt lgkmcnt(" #n ")" ::: "memory")
; #define PG8_BAR __builtin_amdgcn_s_barrier()
; #define PG8_SCHED __builtin_amdgcn_sched_barrier(0)
; template <class Epi, class Sched, bool ALIGN_EPI = false, bool SP2 = false>
; __device__ __forceinline__ void gemm_phase(PG8_LAS unsigned char* lds, const Gemm g, const Sched& S, const Epi& E) {
;     ...
;         for (int t = 0; t < nt; t += 2) {
;     ...
;             PG8_LDA(At, 1, 1); PG8_STAGE(PG8_SB(1, 0), b3, voffB); PG8_STAGE(PG8_SB(1, 1), b3 + hstep, voffB); PG8_STAGE(PG8_SA(1, 0), a3, voffA);
;             PG8_WAIT_V(8); PG8_WAIT_L(0); PG8_BAR; PG8_MMA(1, 0, At, B0); PG8_MMA(1, 1, At, B1); PG8_BAR; PG8_SCHED;
	s_add_i32 s34, s55, s45
	v_lshl_add_u64 v[214:215], v[214:215], 0, s[88:89]
	s_mov_b32 m0, s34
	ds_read_b128 v[182:185], v155 offset:49152
	ds_read_b128 v[186:189], v155 offset:50176
	ds_read_b128 v[190:193], v155 offset:51200
	ds_read_b128 v[194:197], v155 offset:52224
	ds_read_b128 v[198:201], v155 offset:53248
	ds_read_b128 v[202:205], v155 offset:54272
	ds_read_b128 v[206:209], v155 offset:55296
	ds_read_b128 v[210:213], v155 offset:56320
	global_load_lds_dwordx4 v[214:215], off
	s_add_i32 m0, s34, 0x2000
	s_add_u32 s30, s30, 0x40080
	v_lshl_add_u64 v[214:215], v[216:217], 0, s[88:89]
	s_addc_u32 s31, s31, 0
	s_add_i32 s34, s60, s45
	global_load_lds_dwordx4 v[214:215], off
	v_lshl_add_u64 v[214:215], s[30:31], 0, v[138:139]
	s_mov_b32 m0, s34
	s_nop 0
	global_load_lds_dwordx4 v[214:215], off
	v_lshl_add_u64 v[214:215], s[30:31], 0, v[142:143]
	s_add_i32 m0, s34, 0x2000
	s_nop 0
	global_load_lds_dwordx4 v[214:215], off
	v_lshl_add_u64 v[214:215], v[218:219], 0, s[88:89]
	s_mov_b32 m0, s54
	s_nop 0
	global_load_lds_dwordx4 v[214:215], off
	v_lshl_add_u64 v[214:215], v[220:221], 0, s[88:89]
	s_mov_b32 m0, s56
	s_nop 0
	global_load_lds_dwordx4 v[214:215], off
	s_waitcnt vmcnt(8)
	s_waitcnt lgkmcnt(0)
	s_barrier
	s_setprio 1
	s_waitcnt lgkmcnt(0)
	v_mfma_f32_16x16x32_bf16 v[56:59], v[80:83], v[182:185], v[56:59]
	v_mfma_f32_16x16x32_bf16 v[48:51], v[148:151], v[182:185], v[48:51]
	v_mfma_f32_16x16x32_bf16 v[40:43], v[80:83], v[190:193], v[40:43]
	v_mfma_f32_16x16x32_bf16 v[32:35], v[148:151], v[190:193], v[32:35]
	v_mfma_f32_16x16x32_bf16 v[24:27], v[80:83], v[198:201], v[24:27]
	v_mfma_f32_16x16x32_bf16 v[16:19], v[148:151], v[198:201], v[16:19]
	v_mfma_f32_16x16x32_bf16 v[8:11], v[80:83], v[206:209], v[8:11]
	v_mfma_f32_16x16x32_bf16 v[0:3], v[148:151], v[206:209], v[0:3]
	v_mfma_f32_16x16x32_bf16 v[56:59], v[84:87], v[186:189], v[56:59]
	v_mfma_f32_16x16x32_bf16 v[48:51], v[156:159], v[186:189], v[48:51]
	v_mfma_f32_16x16x32_bf16 v[40:43], v[84:87], v[194:197], v[40:43]
	v_mfma_f32_16x16x32_bf16 v[32:35], v[156:159], v[194:197], v[32:35]
	v_mfma_f32_16x16x32_bf16 v[24:27], v[84:87], v[202:205], v[24:27]
	v_mfma_f32_16x16x32_bf16 v[16:19], v[156:159], v[202:205], v[16:19]
	v_mfma_f32_16x16x32_bf16 v[8:11], v[84:87], v[210:213], v[8:11]
	v_mfma_f32_16x16x32_bf16 v[0:3], v[156:159], v[210:213], v[0:3]
	s_setprio 0
	s_setprio 1
	v_mfma_f32_16x16x32_bf16 v[60:63], v[160:163], v[182:185], v[60:63]
	v_mfma_f32_16x16x32_bf16 v[52:55], v[168:171], v[182:185], v[52:55]
	v_mfma_f32_16x16x32_bf16 v[44:47], v[160:163], v[190:193], v[44:47]
	v_mfma_f32_16x16x32_bf16 v[36:39], v[168:171], v[190:193], v[36:39]
	v_mfma_f32_16x16x32_bf16 v[28:31], v[160:163], v[198:201], v[28:31]
	v_mfma_f32_16x16x32_bf16 v[20:23], v[168:171], v[198:201], v[20:23]
	v_mfma_f32_16x16x32_bf16 v[12:15], v[160:163], v[206:209], v[12:15]
	v_mfma_f32_16x16x32_bf16 v[4:7], v[168:171], v[206:209], v[4:7]
	v_mfma_f32_16x16x32_bf16 v[60:63], v[164:167], v[186:189], v[60:63]
	v_mfma_f32_16x16x32_bf16 v[52:55], v[172:175], v[186:189], v[52:55]
	v_mfma_f32_16x16x32_bf16 v[44:47], v[164:167], v[194:197], v[44:47]
	v_mfma_f32_16x16x32_bf16 v[36:39], v[172:175], v[194:197], v[36:39]
	v_mfma_f32_16x16x32_bf16 v[28:31], v[164:167], v[202:205], v[28:31]
	v_mfma_f32_16x16x32_bf16 v[20:23], v[172:175], v[202:205], v[20:23]
	v_mfma_f32_16x16x32_bf16 v[12:15], v[164:167], v[210:213], v[12:15]
	v_mfma_f32_16x16x32_bf16 v[4:7], v[172:175], v[210:213], v[4:7]
	s_add_i32 s62, s62, 2
	s_add_u32 s58, s58, 0x100
	s_addc_u32 s59, s59, 0
	s_add_u32 s28, s28, 0x100
	s_addc_u32 s29, s29, 0
	s_cmp_gt_u32 s62, 13
	s_setprio 0
	s_barrier
	s_cbranch_scc0 .LBB0_1089
	s_and_b64 vcc, exec, s[14:15]
	s_cbranch_vccz .LBB0_1092
	s_barrier

; #define PG8_STAGE(bufoff, gbase, voff) do { _Pragma("unroll") for (int _i = 0; _i < 2; ++_i) \
;         __builtin_amdgcn_global_load_lds((const unsigned*)((const char*)(gbase) + (voff)[_i]), (PG8_LAS unsigned*)(lds + (bufoff) + ldsw + _i * 8192), 16, 0, 0); } while (0)
; #define PG8_LDA(dst, b, h) do { _Pragma("unroll") for (int m = 0; m < 4; ++m) _Pragma("unroll") for (int k = 0; k < 2; ++k) dst[m][k] = *(const PG8_LAS bf16x8*)(lds + PG8_SA(b, h) + aoff + m * 2048 + k * 1024); } while (0)
; #define PG8_LDB(dst, b, h) do { _Pragma("unroll") for (int n = 0; n < 2; ++n) _Pragma("unroll") for (int k = 0; k < 2; ++k) dst[n][k] = *(const PG8_LAS bf16x8*)(lds + PG8_SB(b, h) + boff + n * 2048 + k * 1024); } while (0)
; #define PG8_MMA(ai, bj, At, Bt) do { __builtin_amdgcn_s_setprio(1); _Pragma("unroll") for (int m = 0; m < 4; ++m) _Pragma("unroll") for (int n = 0; n < 2; ++n) _Pragma("unroll") for (int k = 0; k < 2; ++k) \
;         acc[ai][bj][m][n] = __builtin_amdgcn_mfma_f32_16x16x32_bf16(Bt[n][k], At[m][k], acc[ai][bj][m][n], 0, 0, 0); __builtin_amdgcn_s_setprio(0); } while (0)
; #define PG8_WAIT_V(n) asm volatile("s_waitcnt vmcnt(" #n ")" ::: "memory")
; #define PG8_WAIT_L(n) asm volatile("s_waitcnt lgkmcnt(" #n ")" ::: "memory")
; #define PG8_BAR __builtin_amdgcn_s_barrier()
; #define PG8_SCHED __builtin_amdgcn_sched_barrier(0)
; template <class Epi, class Sched, bool ALIGN_EPI = false, bool SP2 = false>
; __device__ __forceinline__ void gemm_phase(PG8_LAS unsigned char* lds, const Gemm g, const Sched& S, const Epi& E) {
;     ...
;             const bool last = (t == nt - 2);
;             const char* a1 = cA + (size_t)(t + 1) * kstep;
;             const char* a2 = last ? nA : cA + (size_t)(t + 2) * kstep; const char* b2 = last ? nB : cB + (size_t)(t + 2) * kstep;
;             const char* a3 = a2 + kstep; const char* b3 = b2 + kstep;
;             if (last && has_next) S.a_ready(nxt);
;             if constexpr (SP2) {
;             PG8_LDB(B0, 0, 0); PG8_LDB(B1, 0, 1); PG8_SCHED; PG8_LDA(At, 0, 0); PG8_STAGE(PG8_SA(1, 1), a1 + hstep, voffA);
;             PG8_WAIT_V(8); PG8_WAIT_L(0); PG8_BAR; PG8_MMA(0, 0, At, B0); PG8_MMA(0, 1, At, B1); PG8_BAR; PG8_SCHED;
;             PG8_LDA(At, 0, 1); PG8_STAGE(PG8_SB(0, 0), b2, voffB); PG8_STAGE(PG8_SB(0, 1), b2 + hstep, voffB); PG8_STAGE(PG8_SA(0, 0), a2, voffA);
.LBB0_1178:
	s_add_u32 s12, s10, 0x100
	s_addc_u32 s13, s11, 0
	s_add_i32 s55, 0, 0x10000
	s_cmp_eq_u32 s62, 40
	s_cselect_b32 s39, s1, s13
	s_cselect_b32 s38, s0, s12
	s_cselect_b32 s37, s15, s59
	s_cselect_b32 s36, s14, s58
	s_add_i32 s60, 0, 0x14000
	v_add_u32_e32 v68, s55, v235
	v_add_u32_e32 v156, s60, v235
	ds_read_b128 v[48:51], v68
	ds_read_b128 v[60:63], v68 offset:1024
	ds_read_b128 v[64:67], v68 offset:2048
	ds_read_b128 v[68:71], v68 offset:3072
	ds_read_b128 v[144:147], v156
	ds_read_b128 v[148:151], v156 offset:1024
	ds_read_b128 v[152:155], v156 offset:2048
	ds_read_b128 v[156:159], v156 offset:3072
	v_lshl_add_u64 v[208:209], s[10:11], 0, v[190:191]
	s_add_i32 m0, s45, 0xc000
	ds_read_b128 v[160:163], v237
	ds_read_b128 v[164:167], v237 offset:1024
	ds_read_b128 v[168:171], v237 offset:2048
	ds_read_b128 v[172:175], v237 offset:3072
	ds_read_b128 v[192:195], v237 offset:4096
	ds_read_b128 v[196:199], v237 offset:5120
	ds_read_b128 v[200:203], v237 offset:6144
	ds_read_b128 v[204:207], v237 offset:7168
	global_load_lds_dwordx4 v[208:209], off
	v_lshl_add_u64 v[208:209], s[10:11], 0, v[188:189]
	s_add_i32 m0, s45, 0xe000
	s_nop 0
	global_load_lds_dwordx4 v[208:209], off
	s_waitcnt vmcnt(8)
	s_waitcnt lgkmcnt(0)
	s_barrier
	s_setprio 1
	s_waitcnt lgkmcnt(0)
	v_mfma_f32_16x16x32_bf16 v[140:143], v[48:51], v[160:163], v[140:143]
	v_mfma_f32_16x16x32_bf16 v[136:139], v[64:67], v[160:163], v[136:139]
	v_mfma_f32_16x16x32_bf16 v[124:127], v[48:51], v[168:171], v[124:127]
	v_mfma_f32_16x16x32_bf16 v[120:123], v[64:67], v[168:171], v[120:123]
	v_mfma_f32_16x16x32_bf16 v[108:111], v[48:51], v[192:195], v[108:111]
	v_mfma_f32_16x16x32_bf16 v[104:107], v[64:67], v[192:195], v[104:107]
	v_mfma_f32_16x16x32_bf16 v[92:95], v[48:51], v[200:203], v[92:95]
	v_mfma_f32_16x16x32_bf16 v[88:91], v[64:67], v[200:203], v[88:91]
	v_mfma_f32_16x16x32_bf16 v[140:143], v[60:63], v[164:167], v[140:143]
	v_mfma_f32_16x16x32_bf16 v[136:139], v[68:71], v[164:167], v[136:139]
	v_mfma_f32_16x16x32_bf16 v[124:127], v[60:63], v[172:175], v[124:127]
	v_mfma_f32_16x16x32_bf16 v[120:123], v[68:71], v[172:175], v[120:123]
	v_mfma_f32_16x16x32_bf16 v[108:111], v[60:63], v[196:199], v[108:111]
	v_mfma_f32_16x16x32_bf16 v[104:107], v[68:71], v[196:199], v[104:107]
	v_mfma_f32_16x16x32_bf16 v[92:95], v[60:63], v[204:207], v[92:95]
	v_mfma_f32_16x16x32_bf16 v[88:91], v[68:71], v[204:207], v[88:91]
	s_setprio 0
	s_setprio 1
	v_mfma_f32_16x16x32_bf16 v[132:135], v[144:147], v[160:163], v[132:135]
	v_mfma_f32_16x16x32_bf16 v[128:131], v[152:155], v[160:163], v[128:131]
	v_mfma_f32_16x16x32_bf16 v[116:119], v[144:147], v[168:171], v[116:119]
	v_mfma_f32_16x16x32_bf16 v[112:115], v[152:155], v[168:171], v[112:115]
	v_mfma_f32_16x16x32_bf16 v[100:103], v[144:147], v[192:195], v[100:103]
	v_mfma_f32_16x16x32_bf16 v[96:99], v[152:155], v[192:195], v[96:99]
	v_mfma_f32_16x16x32_bf16 v[84:87], v[144:147], v[200:203], v[84:87]
	v_mfma_f32_16x16x32_bf16 v[80:83], v[152:155], v[200:203], v[80:83]
	v_mfma_f32_16x16x32_bf16 v[132:135], v[148:151], v[164:167], v[132:135]
	v_mfma_f32_16x16x32_bf16 v[128:131], v[156:159], v[164:167], v[128:131]
	v_mfma_f32_16x16x32_bf16 v[116:119], v[148:151], v[172:175], v[116:119]
	v_mfma_f32_16x16x32_bf16 v[112:115], v[156:159], v[172:175], v[112:115]
	v_mfma_f32_16x16x32_bf16 v[100:103], v[148:151], v[196:199], v[100:103]
	v_mfma_f32_16x16x32_bf16 v[96:99], v[156:159], v[196:199], v[96:99]
	v_mfma_f32_16x16x32_bf16 v[84:87], v[148:151], v[204:207], v[84:87]
	v_mfma_f32_16x16x32_bf16 v[80:83], v[156:159], v[204:207], v[80:83]
	s_setprio 0
	s_barrier
	s_add_i32 s10, s55, s44
	v_lshl_add_u64 v[208:209], s[36:37], 0, v[176:177]
	s_mov_b32 m0, s10
	ds_read_b128 v[160:163], v237 offset:16384
	ds_read_b128 v[164:167], v237 offset:17408
	ds_read_b128 v[168:171], v237 offset:18432
	ds_read_b128 v[172:175], v237 offset:19456
	ds_read_b128 v[192:195], v237 offset:20480
	ds_read_b128 v[196:199], v237 offset:21504
	ds_read_b128 v[200:203], v237 offset:22528
	ds_read_b128 v[204:207], v237 offset:23552
	global_load_lds_dwordx4 v[208:209], off
	s_add_i32 m0, s10, 0x2000
	s_add_u32 s10, s36, 0xb0000
	v_lshl_add_u64 v[210:211], s[36:37], 0, v[182:183]
	s_addc_u32 s11, s37, 0
	s_add_i32 s55, s60, s44
	global_load_lds_dwordx4 v[210:211], off
	v_lshl_add_u64 v[212:213], s[10:11], 0, v[176:177]
	s_mov_b32 m0, s55
	v_lshl_add_u64 v[214:215], s[38:39], 0, v[184:185]
	global_load_lds_dwordx4 v[212:213], off
	v_lshl_add_u64 v[212:213], s[10:11], 0, v[182:183]
	s_add_i32 m0, s55, 0x2000
	s_nop 0
	global_load_lds_dwordx4 v[212:213], off
	v_lshl_add_u64 v[212:213], s[38:39], 0, v[186:187]
	s_mov_b32 m0, s45
	s_nop 0
	global_load_lds_dwordx4 v[212:213], off
	s_mov_b32 m0, s46
	s_nop 0
	global_load_lds_dwordx4 v[214:215], off
	s_waitcnt vmcnt(8)
	s_waitcnt lgkmcnt(0)
	s_barrier
; #define PG8_STAGE(bufoff, gbase, voff) do { _Pragma("unroll") for (int _i = 0; _i < 2; ++_i) \
;         __builtin_amdgcn_global_load_lds((const unsigned*)((const char*)(gbase) + (voff)[_i]), (PG8_LAS unsigned*)(lds + (bufoff) + ldsw + _i * 8192), 16, 0, 0); } while (0)
; #define PG8_LDA(dst, b, h) do { _Pragma("unroll") for (int m = 0; m < 4; ++m) _Pragma("unroll") for (int k = 0; k < 2; ++k) dst[m][k] = *(const PG8_LAS bf16x8*)(lds + PG8_SA(b, h) + aoff + m * 2048 + k * 1024); } while (0)
; #define PG8_LDB(dst, b, h) do { _Pragma("unroll") for (int n = 0; n < 2; ++n) _Pragma("unroll") for (int k = 0; k < 2; ++k) dst[n][k] = *(const PG8_LAS bf16x8*)(lds + PG8_SB(b, h) + boff + n * 2048 + k * 1024); } while (0)
; #define PG8_MMA(ai, bj, At, Bt) do { __builtin_amdgcn_s_setprio(1); _Pragma("unroll") for (int m = 0; m < 4; ++m) _Pragma("unroll") for (int n = 0; n < 2; ++n) _Pragma("unroll") for (int k = 0; k < 2; ++k) \
;         acc[ai][bj][m][n] = __builtin_amdgcn_mfma_f32_16x16x32_bf16(Bt[n][k], At[m][k], acc[ai][bj][m][n], 0, 0, 0); __builtin_amdgcn_s_setprio(0); } while (0)
; #define PG8_WAIT_V(n) asm volatile("s_waitcnt vmcnt(" #n ")" ::: "memory")
; #define PG8_WAIT_L(n) asm volatile("s_waitcnt lgkmcnt(" #n ")" ::: "memory")
; #define PG8_BAR __builtin_amdgcn_s_barrier()
; #define PG8_SCHED __builtin_amdgcn_sched_barrier(0)
; template <class Epi, class Sched, bool ALIGN_EPI = false, bool SP2 = false>
; __device__ __forceinline__ void gemm_phase(PG8_LAS unsigned char* lds, const Gemm g, const Sched& S, const Epi& E) {
;     ...
;             PG8_WAIT_V(8); PG8_WAIT_L(0); PG8_BAR; PG8_MMA(1, 0, At, B0); PG8_MMA(1, 1, At, B1); PG8_BAR; PG8_SCHED;
;             PG8_LDB(B0, 1, 0); PG8_LDB(B1, 1, 1); PG8_SCHED; PG8_LDA(At, 1, 0); PG8_STAGE(PG8_SA(0, 1), a2 + hstep, voffA);
;             PG8_WAIT_V(8); PG8_WAIT_L(0); PG8_BAR; PG8_MMA(0, 0, At, B0); PG8_MMA(0, 1, At, B1); PG8_BAR; PG8_SCHED;
	s_setprio 1
	s_waitcnt lgkmcnt(0)
	v_mfma_f32_16x16x32_bf16 v[76:79], v[48:51], v[160:163], v[76:79]
	v_mfma_f32_16x16x32_bf16 v[72:75], v[64:67], v[160:163], v[72:75]
	v_mfma_f32_16x16x32_bf16 v[44:47], v[48:51], v[168:171], v[44:47]
	v_mfma_f32_16x16x32_bf16 v[40:43], v[64:67], v[168:171], v[40:43]
	v_mfma_f32_16x16x32_bf16 v[28:31], v[48:51], v[192:195], v[28:31]
	v_mfma_f32_16x16x32_bf16 v[24:27], v[64:67], v[192:195], v[24:27]
	v_mfma_f32_16x16x32_bf16 v[12:15], v[48:51], v[200:203], v[12:15]
	v_mfma_f32_16x16x32_bf16 v[8:11], v[64:67], v[200:203], v[8:11]
	v_mfma_f32_16x16x32_bf16 v[76:79], v[60:63], v[164:167], v[76:79]
	v_mfma_f32_16x16x32_bf16 v[72:75], v[68:71], v[164:167], v[72:75]
	v_mfma_f32_16x16x32_bf16 v[44:47], v[60:63], v[172:175], v[44:47]
	v_mfma_f32_16x16x32_bf16 v[40:43], v[68:71], v[172:175], v[40:43]
	v_mfma_f32_16x16x32_bf16 v[28:31], v[60:63], v[196:199], v[28:31]
	v_mfma_f32_16x16x32_bf16 v[24:27], v[68:71], v[196:199], v[24:27]
	v_mfma_f32_16x16x32_bf16 v[12:15], v[60:63], v[204:207], v[12:15]
	v_mfma_f32_16x16x32_bf16 v[8:11], v[68:71], v[204:207], v[8:11]
	s_setprio 0
	s_setprio 1
	v_mfma_f32_16x16x32_bf16 v[52:55], v[152:155], v[160:163], v[52:55]
	v_mfma_f32_16x16x32_bf16 v[36:39], v[144:147], v[168:171], v[36:39]
	v_mfma_f32_16x16x32_bf16 v[32:35], v[152:155], v[168:171], v[32:35]
	v_mfma_f32_16x16x32_bf16 v[20:23], v[144:147], v[192:195], v[20:23]
	v_mfma_f32_16x16x32_bf16 v[16:19], v[152:155], v[192:195], v[16:19]
	v_mfma_f32_16x16x32_bf16 v[4:7], v[144:147], v[200:203], v[4:7]
	v_mfma_f32_16x16x32_bf16 v[0:3], v[152:155], v[200:203], v[0:3]
	v_mfma_f32_16x16x32_bf16 v[48:51], v[144:147], v[160:163], v[56:59]
	v_mfma_f32_16x16x32_bf16 v[52:55], v[156:159], v[164:167], v[52:55]
	v_mfma_f32_16x16x32_bf16 v[36:39], v[148:151], v[172:175], v[36:39]
	v_mfma_f32_16x16x32_bf16 v[32:35], v[156:159], v[172:175], v[32:35]
	v_mfma_f32_16x16x32_bf16 v[20:23], v[148:151], v[196:199], v[20:23]
	v_mfma_f32_16x16x32_bf16 v[16:19], v[156:159], v[196:199], v[16:19]
	v_mfma_f32_16x16x32_bf16 v[4:7], v[148:151], v[204:207], v[4:7]
	v_mfma_f32_16x16x32_bf16 v[0:3], v[156:159], v[204:207], v[0:3]
	v_mfma_f32_16x16x32_bf16 v[48:51], v[148:151], v[164:167], v[48:51]
	s_setprio 0
	s_barrier
	s_add_i32 s55, 0, 0x18000
	s_add_i32 s60, 0, 0x1c000
	v_add_u32_e32 v68, s55, v235
	v_add_u32_e32 v156, s60, v235
	ds_read_b128 v[56:59], v68
	ds_read_b128 v[60:63], v68 offset:1024
	ds_read_b128 v[64:67], v68 offset:2048
	ds_read_b128 v[68:71], v68 offset:3072
	ds_read_b128 v[144:147], v156
	ds_read_b128 v[148:151], v156 offset:1024
	ds_read_b128 v[152:155], v156 offset:2048
	ds_read_b128 v[156:159], v156 offset:3072
	s_add_u32 s10, s38, 0xb0000
	s_addc_u32 s11, s39, 0
	s_mov_b32 m0, s49
	v_lshl_add_u64 v[216:217], s[10:11], 0, v[186:187]
	ds_read_b128 v[160:163], v237 offset:32768
	ds_read_b128 v[164:167], v237 offset:33792
	ds_read_b128 v[168:171], v237 offset:34816
	ds_read_b128 v[172:175], v237 offset:35840
	ds_read_b128 v[192:195], v237 offset:36864
	ds_read_b128 v[196:199], v237 offset:37888
	ds_read_b128 v[200:203], v237 offset:38912
	ds_read_b128 v[204:207], v237 offset:39936
	global_load_lds_dwordx4 v[216:217], off
	v_lshl_add_u64 v[216:217], s[10:11], 0, v[184:185]
	s_mov_b32 m0, s51
	s_nop 0
	global_load_lds_dwordx4 v[216:217], off
	s_waitcnt vmcnt(8)
	s_waitcnt lgkmcnt(0)
	s_barrier
	s_setprio 1
	s_waitcnt lgkmcnt(0)
	v_mfma_f32_16x16x32_bf16 v[140:143], v[56:59], v[160:163], v[140:143]
	v_mfma_f32_16x16x32_bf16 v[136:139], v[64:67], v[160:163], v[136:139]
	v_mfma_f32_16x16x32_bf16 v[124:127], v[56:59], v[168:171], v[124:127]
	v_mfma_f32_16x16x32_bf16 v[120:123], v[64:67], v[168:171], v[120:123]
	v_mfma_f32_16x16x32_bf16 v[108:111], v[56:59], v[192:195], v[108:111]
	v_mfma_f32_16x16x32_bf16 v[104:107], v[64:67], v[192:195], v[104:107]
	v_mfma_f32_16x16x32_bf16 v[92:95], v[56:59], v[200:203], v[92:95]
	v_mfma_f32_16x16x32_bf16 v[88:91], v[64:67], v[200:203], v[88:91]
	v_mfma_f32_16x16x32_bf16 v[140:143], v[60:63], v[164:167], v[140:143]
	v_mfma_f32_16x16x32_bf16 v[136:139], v[68:71], v[164:167], v[136:139]
	v_mfma_f32_16x16x32_bf16 v[124:127], v[60:63], v[172:175], v[124:127]
	v_mfma_f32_16x16x32_bf16 v[120:123], v[68:71], v[172:175], v[120:123]
	v_mfma_f32_16x16x32_bf16 v[108:111], v[60:63], v[196:199], v[108:111]
	v_mfma_f32_16x16x32_bf16 v[104:107], v[68:71], v[196:199], v[104:107]
	v_mfma_f32_16x16x32_bf16 v[92:95], v[60:63], v[204:207], v[92:95]
	v_mfma_f32_16x16x32_bf16 v[88:91], v[68:71], v[204:207], v[88:91]
	s_setprio 0
	s_setprio 1
	v_mfma_f32_16x16x32_bf16 v[132:135], v[144:147], v[160:163], v[132:135]
	v_mfma_f32_16x16x32_bf16 v[128:131], v[152:155], v[160:163], v[128:131]
	v_mfma_f32_16x16x32_bf16 v[116:119], v[144:147], v[168:171], v[116:119]
	v_mfma_f32_16x16x32_bf16 v[112:115], v[152:155], v[168:171], v[112:115]
	v_mfma_f32_16x16x32_bf16 v[100:103], v[144:147], v[192:195], v[100:103]
	v_mfma_f32_16x16x32_bf16 v[96:99], v[152:155], v[192:195], v[96:99]
	v_mfma_f32_16x16x32_bf16 v[84:87], v[144:147], v[200:203], v[84:87]
	v_mfma_f32_16x16x32_bf16 v[80:83], v[152:155], v[200:203], v[80:83]
	v_mfma_f32_16x16x32_bf16 v[132:135], v[148:151], v[164:167], v[132:135]
	v_mfma_f32_16x16x32_bf16 v[128:131], v[156:159], v[164:167], v[128:131]
	v_mfma_f32_16x16x32_bf16 v[116:119], v[148:151], v[172:175], v[116:119]
	v_mfma_f32_16x16x32_bf16 v[112:115], v[156:159], v[172:175], v[112:115]
	v_mfma_f32_16x16x32_bf16 v[100:103], v[148:151], v[196:199], v[100:103]
	v_mfma_f32_16x16x32_bf16 v[96:99], v[156:159], v[196:199], v[96:99]
	v_mfma_f32_16x16x32_bf16 v[84:87], v[148:151], v[204:207], v[84:87]
	v_mfma_f32_16x16x32_bf16 v[80:83], v[156:159], v[204:207], v[80:83]
	s_setprio 0
	s_barrier
; #define PG8_STAGE(bufoff, gbase, voff) do { _Pragma("unroll") for (int _i = 0; _i < 2; ++_i) \
;         __builtin_amdgcn_global_load_lds((const unsigned*)((const char*)(gbase) + (voff)[_i]), (PG8_LAS unsigned*)(lds + (bufoff) + ldsw + _i * 8192), 16, 0, 0); } while (0)
; #define PG8_LDA(dst, b, h) do { _Pragma("unroll") for (int m = 0; m < 4; ++m) _Pragma("unroll") for (int k = 0; k < 2; ++k) dst[m][k] = *(const PG8_LAS bf16x8*)(lds + PG8_SA(b, h) + aoff + m * 2048 + k * 1024); } while (0)
; #define PG8_MMA(ai, bj, At, Bt) do { __builtin_amdgcn_s_setprio(1); _Pragma("unroll") for (int m = 0; m < 4; ++m) _Pragma("unroll") for (int n = 0; n < 2; ++n) _Pragma("unroll") for (int k = 0; k < 2; ++k) \
;         acc[ai][bj][m][n] = __builtin_amdgcn_mfma_f32_16x16x32_bf16(Bt[n][k], At[m][k], acc[ai][bj][m][n], 0, 0, 0); __builtin_amdgcn_s_setprio(0); } while (0)
; #define PG8_WAIT_V(n) asm volatile("s_waitcnt vmcnt(" #n ")" ::: "memory")
; #define PG8_WAIT_L(n) asm volatile("s_waitcnt lgkmcnt(" #n ")" ::: "memory")
; #define PG8_BAR __builtin_amdgcn_s_barrier()
; #define PG8_SCHED __builtin_amdgcn_sched_barrier(0)
; template <class Epi, class Sched, bool ALIGN_EPI = false, bool SP2 = false>
; __device__ __forceinline__ void gemm_phase(PG8_LAS unsigned char* lds, const Gemm g, const Sched& S, const Epi& E) {
;     ...
;         for (int t = 0; t < nt; t += 2) {
;     ...
;             PG8_LDA(At, 1, 1); PG8_STAGE(PG8_SB(1, 0), b3, voffB); PG8_STAGE(PG8_SB(1, 1), b3 + hstep, voffB); PG8_STAGE(PG8_SA(1, 0), a3, voffA);
;             PG8_WAIT_V(8); PG8_WAIT_L(0); PG8_BAR; PG8_MMA(1, 0, At, B0); PG8_MMA(1, 1, At, B1); PG8_BAR; PG8_SCHED;
	s_add_i32 s10, s55, s44
	v_lshl_add_u64 v[208:209], v[208:209], 0, s[88:89]
	s_mov_b32 m0, s10
	ds_read_b128 v[160:163], v237 offset:49152
	ds_read_b128 v[164:167], v237 offset:50176
	ds_read_b128 v[168:171], v237 offset:51200
	ds_read_b128 v[172:175], v237 offset:52224
	ds_read_b128 v[192:195], v237 offset:53248
	ds_read_b128 v[196:199], v237 offset:54272
	ds_read_b128 v[200:203], v237 offset:55296
	ds_read_b128 v[204:207], v237 offset:56320
	global_load_lds_dwordx4 v[208:209], off
	s_add_i32 m0, s10, 0x2000
	s_add_u32 s10, s36, 0xb0080
	v_lshl_add_u64 v[208:209], v[210:211], 0, s[88:89]
	s_addc_u32 s11, s37, 0
	s_add_i32 s36, s60, s44
	global_load_lds_dwordx4 v[208:209], off
	v_lshl_add_u64 v[208:209], s[10:11], 0, v[176:177]
	s_mov_b32 m0, s36
	s_nop 0
	global_load_lds_dwordx4 v[208:209], off
	v_lshl_add_u64 v[208:209], s[10:11], 0, v[182:183]
	s_add_i32 m0, s36, 0x2000
	s_nop 0
	global_load_lds_dwordx4 v[208:209], off
	v_lshl_add_u64 v[208:209], v[212:213], 0, s[88:89]
	s_mov_b32 m0, s16
	s_nop 0
	global_load_lds_dwordx4 v[208:209], off
	v_lshl_add_u64 v[208:209], v[214:215], 0, s[88:89]
	s_mov_b32 m0, s17
	s_nop 0
	global_load_lds_dwordx4 v[208:209], off
	s_waitcnt vmcnt(8)
	s_waitcnt lgkmcnt(0)
	s_barrier
	s_setprio 1
	s_waitcnt lgkmcnt(0)
	v_mfma_f32_16x16x32_bf16 v[76:79], v[56:59], v[160:163], v[76:79]
	v_mfma_f32_16x16x32_bf16 v[72:75], v[64:67], v[160:163], v[72:75]
	v_mfma_f32_16x16x32_bf16 v[44:47], v[56:59], v[168:171], v[44:47]
	v_mfma_f32_16x16x32_bf16 v[40:43], v[64:67], v[168:171], v[40:43]
	v_mfma_f32_16x16x32_bf16 v[28:31], v[56:59], v[192:195], v[28:31]
	v_mfma_f32_16x16x32_bf16 v[24:27], v[64:67], v[192:195], v[24:27]
	v_mfma_f32_16x16x32_bf16 v[12:15], v[56:59], v[200:203], v[12:15]
	v_mfma_f32_16x16x32_bf16 v[8:11], v[64:67], v[200:203], v[8:11]
	v_mfma_f32_16x16x32_bf16 v[76:79], v[60:63], v[164:167], v[76:79]
	v_mfma_f32_16x16x32_bf16 v[72:75], v[68:71], v[164:167], v[72:75]
	v_mfma_f32_16x16x32_bf16 v[44:47], v[60:63], v[172:175], v[44:47]
	v_mfma_f32_16x16x32_bf16 v[40:43], v[68:71], v[172:175], v[40:43]
	v_mfma_f32_16x16x32_bf16 v[28:31], v[60:63], v[196:199], v[28:31]
	v_mfma_f32_16x16x32_bf16 v[24:27], v[68:71], v[196:199], v[24:27]
	v_mfma_f32_16x16x32_bf16 v[12:15], v[60:63], v[204:207], v[12:15]
	v_mfma_f32_16x16x32_bf16 v[8:11], v[68:71], v[204:207], v[8:11]
	s_setprio 0
	s_setprio 1
	v_mfma_f32_16x16x32_bf16 v[48:51], v[144:147], v[160:163], v[48:51]
	v_mfma_f32_16x16x32_bf16 v[56:59], v[148:151], v[164:167], v[48:51]
	v_mfma_f32_16x16x32_bf16 v[48:51], v[152:155], v[160:163], v[52:55]
	v_mfma_f32_16x16x32_bf16 v[36:39], v[144:147], v[168:171], v[36:39]
	v_mfma_f32_16x16x32_bf16 v[32:35], v[152:155], v[168:171], v[32:35]
	v_mfma_f32_16x16x32_bf16 v[20:23], v[144:147], v[192:195], v[20:23]
	v_mfma_f32_16x16x32_bf16 v[16:19], v[152:155], v[192:195], v[16:19]
	v_mfma_f32_16x16x32_bf16 v[4:7], v[144:147], v[200:203], v[4:7]
	v_mfma_f32_16x16x32_bf16 v[0:3], v[152:155], v[200:203], v[0:3]
	v_mfma_f32_16x16x32_bf16 v[52:55], v[156:159], v[164:167], v[48:51]
	v_mfma_f32_16x16x32_bf16 v[36:39], v[148:151], v[172:175], v[36:39]
	v_mfma_f32_16x16x32_bf16 v[32:35], v[156:159], v[172:175], v[32:35]
	v_mfma_f32_16x16x32_bf16 v[20:23], v[148:151], v[196:199], v[20:23]
	v_mfma_f32_16x16x32_bf16 v[16:19], v[156:159], v[196:199], v[16:19]
	v_mfma_f32_16x16x32_bf16 v[4:7], v[148:151], v[204:207], v[4:7]
	v_mfma_f32_16x16x32_bf16 v[0:3], v[156:159], v[204:207], v[0:3]
	s_add_i32 s62, s62, 2
	s_add_u32 s58, s58, 0x100
	s_addc_u32 s59, s59, 0
	s_cmp_gt_u32 s62, 41
	s_mov_b64 s[10:11], s[12:13]
	s_setprio 0
	s_barrier
	s_cbranch_scc0 .LBB0_1178
	s_and_b64 vcc, exec, s[34:35]
	s_cbranch_vccz .LBB0_1181
	s_barrier
